# grid barrier: per-XCC leaders add straight into the polled generation word (release at 8*k), one atomic round trip less per barrier
# speedup vs baseline: 1.0043x; 1.0024x over previous
.LBB0_60:
	s_lshl_b32 s4, s3, 8
	s_mov_b32 s5, 0
	v_lshl_add_u64 v[4:5], v[130:131], 0, s[4:5]
	v_add_co_u32_e32 v4, vcc, 0x1000, v4
	v_mov_b32_e32 v1, 1
	s_nop 0
	v_addc_co_u32_e32 v5, vcc, 0, v5, vcc
	global_atomic_add v1, v[4:5], v1, off offset:1024 sc0
	v_cvt_f32_u32_e32 v3, v0
	v_sub_u32_e32 v4, 0, v0
	v_rcp_iflag_f32_e32 v3, v3
	s_nop 0
	v_mul_f32_e32 v3, 0x4f7ffffe, v3
	v_cvt_u32_f32_e32 v3, v3
	v_mul_lo_u32 v4, v4, v3
	v_mul_hi_u32 v4, v3, v4
	v_add_u32_e32 v3, v3, v4
	s_waitcnt vmcnt(0)
	v_mul_hi_u32 v3, v1, v3
	v_mul_lo_u32 v5, v3, v0
	v_add_u32_e32 v4, 1, v1
	v_sub_u32_e32 v1, v1, v5
	v_add_u32_e32 v6, 1, v3
	v_cmp_ge_u32_e32 vcc, v1, v0
	v_sub_u32_e32 v5, v1, v0
	s_nop 0
	v_cndmask_b32_e32 v3, v3, v6, vcc
	v_cndmask_b32_e32 v1, v1, v5, vcc
	v_add_u32_e32 v5, 1, v3
	v_cmp_ge_u32_e32 vcc, v1, v0
	s_nop 1
	v_cndmask_b32_e32 v1, v3, v5, vcc
	v_mad_u64_u32 v[0:1], s[4:5], v0, v1, v[0:1]
	v_cmp_ne_u32_e32 vcc, v4, v0
	s_and_saveexec_b64 s[4:5], vcc
	s_xor_b64 s[4:5], exec, s[4:5]
	s_cbranch_execz .LBB0_73
	v_add_co_u32_e32 v0, vcc, 0x7000, v128
	s_nop 1
	v_addc_co_u32_e32 v1, vcc, 0, v129, vcc
	global_load_dword v0, v[0:1], off offset:1280 sc1
	s_waitcnt vmcnt(0)
	v_cmp_gt_u32_e32 vcc, 0x8, v0
	s_and_saveexec_b64 s[6:7], vcc
	s_cbranch_execz .LBB0_72
	s_mov_b64 s[8:9], 0x7500
	s_waitcnt lgkmcnt(0)
	v_lshl_add_u64 v[2:3], v[128:129], 0, s[8:9]
	s_mov_b64 s[8:9], 0x4200
	v_lshl_add_u64 v[0:1], v[128:129], 0, s[8:9]
	s_mov_b32 s24, 1
	s_mov_b64 s[8:9], 0
	s_branch .LBB0_64

.LBB0_68:
	s_andn2_b64 s[14:15], s[14:15], exec
	s_and_b64 s[20:21], s[20:21], exec
	s_or_b64 s[14:15], s[14:15], s[20:21]
	s_and_saveexec_b64 s[20:21], s[18:19]
	s_cbranch_execz .LBB0_63
	global_load_dword v4, v[2:3], off sc1
	s_add_i32 s24, s24, 1
	s_or_b64 s[14:15], s[14:15], exec
	s_waitcnt vmcnt(0)
	v_cmp_lt_u32_e32 vcc, 0x7, v4
	s_orn2_b64 s[16:17], vcc, exec
	s_branch .LBB0_63

.LBB0_73:
	s_andn2_saveexec_b64 s[4:5], s[4:5]
	s_cbranch_execz .LBB0_89
	v_add_co_u32_e32 v0, vcc, 0x7000, v128
	buffer_wbl2 sc1
	s_waitcnt lgkmcnt(0)
	s_waitcnt vmcnt(0)
	v_addc_co_u32_e32 v1, vcc, 0, v129, vcc
	v_mov_b32_e32 v3, 1
	global_atomic_add v3, v[0:1], v3, off offset:1280 sc0
	v_cvt_f32_u32_e32 v0, v2
	v_sub_u32_e32 v4, 0, v2
	s_mov_b64 s[4:5], 0x7500
	s_mov_b64 s[6:7], 0
	v_rcp_iflag_f32_e32 v0, v0
	s_nop 0
	v_mul_f32_e32 v0, 0x4f7ffffe, v0
	v_cvt_u32_f32_e32 v5, v0
	v_lshl_add_u64 v[0:1], v[128:129], 0, s[4:5]
	v_mul_lo_u32 v4, v4, v5
	v_mul_hi_u32 v4, v5, v4
	v_add_u32_e32 v4, v5, v4
	s_waitcnt vmcnt(0)
	v_mul_hi_u32 v4, v3, v4
	v_mul_lo_u32 v6, v4, v2
	v_add_u32_e32 v5, 1, v3
	v_sub_u32_e32 v3, v3, v6
	v_add_u32_e32 v7, 1, v4
	v_cmp_ge_u32_e32 vcc, v3, v2
	v_sub_u32_e32 v6, v3, v2
	s_nop 0
	v_cndmask_b32_e32 v4, v4, v7, vcc
	v_cndmask_b32_e32 v3, v3, v6, vcc
	v_add_u32_e32 v6, 1, v4
	v_cmp_ge_u32_e32 vcc, v3, v2
	s_nop 1
	v_cndmask_b32_e32 v4, v4, v6, vcc
	v_mad_u64_u32 v[2:3], s[4:5], v2, v4, v[2:3]
	v_cmp_ne_u32_e32 vcc, v5, v2
	s_and_saveexec_b64 s[4:5], vcc
	s_cbranch_execz .LBB0_86
	global_load_dword v2, v[0:1], off sc1
	s_mov_b64 s[8:9], 0
	s_waitcnt vmcnt(0)
	v_cmp_gt_u32_e32 vcc, 0x8, v2
	s_and_saveexec_b64 s[6:7], vcc
	s_cbranch_execz .LBB0_85
	s_mov_b64 s[8:9], 0x4200
	v_lshl_add_u64 v[2:3], v[128:129], 0, s[8:9]
	s_mov_b32 s22, 1
	s_mov_b64 s[8:9], 0
	s_branch .LBB0_78

.LBB0_83:
	global_load_dword v5, v[0:1], off sc1
	s_add_i32 s22, s22, 1
	s_or_b64 s[14:15], s[14:15], exec
	s_waitcnt vmcnt(0)
	v_cmp_le_u32_e32 vcc, 0x8, v5
	s_orn2_b64 s[18:19], vcc, exec
	s_branch .LBB0_77

.LBB0_128:
	s_lshl_b32 s4, s3, 8
	s_mov_b32 s5, 0
	v_lshl_add_u64 v[4:5], v[130:131], 0, s[4:5]
	v_add_co_u32_e32 v4, vcc, 0x1000, v4
	v_mov_b32_e32 v1, 1
	s_nop 0
	v_addc_co_u32_e32 v5, vcc, 0, v5, vcc
	global_atomic_add v1, v[4:5], v1, off offset:1024 sc0
	v_cvt_f32_u32_e32 v3, v0
	v_sub_u32_e32 v4, 0, v0
	v_rcp_iflag_f32_e32 v3, v3
	s_nop 0
	v_mul_f32_e32 v3, 0x4f7ffffe, v3
	v_cvt_u32_f32_e32 v3, v3
	v_mul_lo_u32 v4, v4, v3
	v_mul_hi_u32 v4, v3, v4
	v_add_u32_e32 v3, v3, v4
	s_waitcnt vmcnt(0)
	v_mul_hi_u32 v3, v1, v3
	v_mul_lo_u32 v5, v3, v0
	v_add_u32_e32 v4, 1, v1
	v_sub_u32_e32 v1, v1, v5
	v_add_u32_e32 v6, 1, v3
	v_cmp_ge_u32_e32 vcc, v1, v0
	v_sub_u32_e32 v5, v1, v0
	s_nop 0
	v_cndmask_b32_e32 v3, v3, v6, vcc
	v_cndmask_b32_e32 v1, v1, v5, vcc
	v_add_u32_e32 v5, 1, v3
	v_cmp_ge_u32_e32 vcc, v1, v0
	s_nop 1
	v_cndmask_b32_e32 v1, v3, v5, vcc
	v_mad_u64_u32 v[0:1], s[4:5], v0, v1, v[0:1]
	v_cmp_ne_u32_e32 vcc, v4, v0
	s_and_saveexec_b64 s[4:5], vcc
	s_xor_b64 s[4:5], exec, s[4:5]
	s_cbranch_execz .LBB0_141
	v_add_co_u32_e32 v0, vcc, 0x7000, v128
	s_nop 1
	v_addc_co_u32_e32 v1, vcc, 0, v129, vcc
	global_load_dword v0, v[0:1], off offset:1280 sc1
	s_waitcnt vmcnt(0)
	v_cmp_gt_u32_e32 vcc, 0x10, v0
	s_and_saveexec_b64 s[6:7], vcc
	s_cbranch_execz .LBB0_140
	s_mov_b64 s[8:9], 0x7500
	s_waitcnt lgkmcnt(0)
	v_lshl_add_u64 v[2:3], v[128:129], 0, s[8:9]
	s_mov_b64 s[8:9], 0x4200
	v_lshl_add_u64 v[0:1], v[128:129], 0, s[8:9]
	s_mov_b32 s24, 1
	s_mov_b64 s[8:9], 0
	s_branch .LBB0_132

.LBB0_136:
	s_andn2_b64 s[14:15], s[14:15], exec
	s_and_b64 s[20:21], s[20:21], exec
	s_or_b64 s[14:15], s[14:15], s[20:21]
	s_and_saveexec_b64 s[20:21], s[18:19]
	s_cbranch_execz .LBB0_131
	global_load_dword v4, v[2:3], off sc1
	s_add_i32 s24, s24, 1
	s_or_b64 s[14:15], s[14:15], exec
	s_waitcnt vmcnt(0)
	v_cmp_lt_u32_e32 vcc, 0xf, v4
	s_orn2_b64 s[16:17], vcc, exec
	s_branch .LBB0_131

.LBB0_141:
	s_andn2_saveexec_b64 s[4:5], s[4:5]
	s_cbranch_execz .LBB0_157
	v_add_co_u32_e32 v0, vcc, 0x7000, v128
	buffer_wbl2 sc1
	s_waitcnt lgkmcnt(0)
	s_waitcnt vmcnt(0)
	v_addc_co_u32_e32 v1, vcc, 0, v129, vcc
	v_mov_b32_e32 v3, 1
	global_atomic_add v3, v[0:1], v3, off offset:1280 sc0
	v_cvt_f32_u32_e32 v0, v2
	v_sub_u32_e32 v4, 0, v2
	s_mov_b64 s[4:5], 0x7500
	s_mov_b64 s[6:7], 0
	v_rcp_iflag_f32_e32 v0, v0
	s_nop 0
	v_mul_f32_e32 v0, 0x4f7ffffe, v0
	v_cvt_u32_f32_e32 v5, v0
	v_lshl_add_u64 v[0:1], v[128:129], 0, s[4:5]
	v_mul_lo_u32 v4, v4, v5
	v_mul_hi_u32 v4, v5, v4
	v_add_u32_e32 v4, v5, v4
	s_waitcnt vmcnt(0)
	v_mul_hi_u32 v4, v3, v4
	v_mul_lo_u32 v6, v4, v2
	v_add_u32_e32 v5, 1, v3
	v_sub_u32_e32 v3, v3, v6
	v_add_u32_e32 v7, 1, v4
	v_cmp_ge_u32_e32 vcc, v3, v2
	v_sub_u32_e32 v6, v3, v2
	s_nop 0
	v_cndmask_b32_e32 v4, v4, v7, vcc
	v_cndmask_b32_e32 v3, v3, v6, vcc
	v_add_u32_e32 v6, 1, v4
	v_cmp_ge_u32_e32 vcc, v3, v2
	s_nop 1
	v_cndmask_b32_e32 v4, v4, v6, vcc
	v_mad_u64_u32 v[2:3], s[4:5], v2, v4, v[2:3]
	v_cmp_ne_u32_e32 vcc, v5, v2
	s_and_saveexec_b64 s[4:5], vcc
	s_cbranch_execz .LBB0_154
	global_load_dword v2, v[0:1], off sc1
	s_mov_b64 s[8:9], 0
	s_waitcnt vmcnt(0)
	v_cmp_gt_u32_e32 vcc, 0x10, v2
	s_and_saveexec_b64 s[6:7], vcc
	s_cbranch_execz .LBB0_153
	s_mov_b64 s[8:9], 0x4200
	v_lshl_add_u64 v[2:3], v[128:129], 0, s[8:9]
	s_mov_b32 s22, 1
	s_mov_b64 s[8:9], 0
	s_branch .LBB0_146

.LBB0_151:
	global_load_dword v5, v[0:1], off sc1
	s_add_i32 s22, s22, 1
	s_or_b64 s[14:15], s[14:15], exec
	s_waitcnt vmcnt(0)
	v_cmp_le_u32_e32 vcc, 0x10, v5
	s_orn2_b64 s[18:19], vcc, exec
	s_branch .LBB0_145

.LBB0_342:
	s_lshl_b32 s4, s3, 8
	s_mov_b32 s5, 0
	v_lshl_add_u64 v[4:5], v[130:131], 0, s[4:5]
	v_add_co_u32_e32 v4, vcc, 0x1000, v4
	v_mov_b32_e32 v1, 1
	s_nop 0
	v_addc_co_u32_e32 v5, vcc, 0, v5, vcc
	global_atomic_add v1, v[4:5], v1, off offset:1024 sc0
	v_cvt_f32_u32_e32 v3, v0
	v_sub_u32_e32 v4, 0, v0
	v_rcp_iflag_f32_e32 v3, v3
	s_nop 0
	v_mul_f32_e32 v3, 0x4f7ffffe, v3
	v_cvt_u32_f32_e32 v3, v3
	v_mul_lo_u32 v4, v4, v3
	v_mul_hi_u32 v4, v3, v4
	v_add_u32_e32 v3, v3, v4
	s_waitcnt vmcnt(0)
	v_mul_hi_u32 v3, v1, v3
	v_mul_lo_u32 v5, v3, v0
	v_add_u32_e32 v4, 1, v1
	v_sub_u32_e32 v1, v1, v5
	v_add_u32_e32 v6, 1, v3
	v_cmp_ge_u32_e32 vcc, v1, v0
	v_sub_u32_e32 v5, v1, v0
	s_nop 0
	v_cndmask_b32_e32 v3, v3, v6, vcc
	v_cndmask_b32_e32 v1, v1, v5, vcc
	v_add_u32_e32 v5, 1, v3
	v_cmp_ge_u32_e32 vcc, v1, v0
	s_nop 1
	v_cndmask_b32_e32 v1, v3, v5, vcc
	v_mad_u64_u32 v[0:1], s[4:5], v0, v1, v[0:1]
	v_cmp_ne_u32_e32 vcc, v4, v0
	s_and_saveexec_b64 s[4:5], vcc
	s_xor_b64 s[4:5], exec, s[4:5]
	s_cbranch_execz .LBB0_355
	v_add_co_u32_e32 v0, vcc, 0x7000, v128
	s_nop 1
	v_addc_co_u32_e32 v1, vcc, 0, v129, vcc
	global_load_dword v0, v[0:1], off offset:1280 sc1
	s_waitcnt vmcnt(0)
	v_cmp_gt_u32_e32 vcc, 0x18, v0
	s_and_saveexec_b64 s[6:7], vcc
	s_cbranch_execz .LBB0_354
	s_mov_b64 s[8:9], 0x7500
	s_waitcnt lgkmcnt(0)
	v_lshl_add_u64 v[2:3], v[128:129], 0, s[8:9]
	s_mov_b64 s[8:9], 0x4200
	v_lshl_add_u64 v[0:1], v[128:129], 0, s[8:9]
	s_mov_b32 s24, 1
	s_mov_b64 s[8:9], 0
	s_branch .LBB0_346

.LBB0_350:
	s_andn2_b64 s[14:15], s[14:15], exec
	s_and_b64 s[20:21], s[20:21], exec
	s_or_b64 s[14:15], s[14:15], s[20:21]
	s_and_saveexec_b64 s[20:21], s[18:19]
	s_cbranch_execz .LBB0_345
	global_load_dword v4, v[2:3], off sc1
	s_add_i32 s24, s24, 1
	s_or_b64 s[14:15], s[14:15], exec
	s_waitcnt vmcnt(0)
	v_cmp_lt_u32_e32 vcc, 0x17, v4
	s_orn2_b64 s[16:17], vcc, exec
	s_branch .LBB0_345

.LBB0_355:
	s_andn2_saveexec_b64 s[4:5], s[4:5]
	s_cbranch_execz .LBB0_371
	v_add_co_u32_e32 v0, vcc, 0x7000, v128
	buffer_wbl2 sc1
	s_waitcnt lgkmcnt(0)
	s_waitcnt vmcnt(0)
	v_addc_co_u32_e32 v1, vcc, 0, v129, vcc
	v_mov_b32_e32 v3, 1
	global_atomic_add v3, v[0:1], v3, off offset:1280 sc0
	v_cvt_f32_u32_e32 v0, v2
	v_sub_u32_e32 v4, 0, v2
	s_mov_b64 s[4:5], 0x7500
	s_mov_b64 s[6:7], 0
	v_rcp_iflag_f32_e32 v0, v0
	s_nop 0
	v_mul_f32_e32 v0, 0x4f7ffffe, v0
	v_cvt_u32_f32_e32 v5, v0
	v_lshl_add_u64 v[0:1], v[128:129], 0, s[4:5]
	v_mul_lo_u32 v4, v4, v5
	v_mul_hi_u32 v4, v5, v4
	v_add_u32_e32 v4, v5, v4
	s_waitcnt vmcnt(0)
	v_mul_hi_u32 v4, v3, v4
	v_mul_lo_u32 v6, v4, v2
	v_add_u32_e32 v5, 1, v3
	v_sub_u32_e32 v3, v3, v6
	v_add_u32_e32 v7, 1, v4
	v_cmp_ge_u32_e32 vcc, v3, v2
	v_sub_u32_e32 v6, v3, v2
	s_nop 0
	v_cndmask_b32_e32 v4, v4, v7, vcc
	v_cndmask_b32_e32 v3, v3, v6, vcc
	v_add_u32_e32 v6, 1, v4
	v_cmp_ge_u32_e32 vcc, v3, v2
	s_nop 1
	v_cndmask_b32_e32 v4, v4, v6, vcc
	v_mad_u64_u32 v[2:3], s[4:5], v2, v4, v[2:3]
	v_cmp_ne_u32_e32 vcc, v5, v2
	s_and_saveexec_b64 s[4:5], vcc
	s_cbranch_execz .LBB0_368
	global_load_dword v2, v[0:1], off sc1
	s_mov_b64 s[8:9], 0
	s_waitcnt vmcnt(0)
	v_cmp_gt_u32_e32 vcc, 0x18, v2
	s_and_saveexec_b64 s[6:7], vcc
	s_cbranch_execz .LBB0_367
	s_mov_b64 s[8:9], 0x4200
	v_lshl_add_u64 v[2:3], v[128:129], 0, s[8:9]
	s_mov_b32 s22, 1
	s_mov_b64 s[8:9], 0
	s_branch .LBB0_360

.LBB0_365:
	global_load_dword v5, v[0:1], off sc1
	s_add_i32 s22, s22, 1
	s_or_b64 s[14:15], s[14:15], exec
	s_waitcnt vmcnt(0)
	v_cmp_le_u32_e32 vcc, 0x18, v5
	s_orn2_b64 s[18:19], vcc, exec
	s_branch .LBB0_359

.LBB0_576:
	s_lshl_b32 s4, s3, 8
	s_mov_b32 s5, 0
	v_lshl_add_u64 v[4:5], v[130:131], 0, s[4:5]
	v_add_co_u32_e32 v4, vcc, 0x1000, v4
	v_mov_b32_e32 v1, 1
	s_nop 0
	v_addc_co_u32_e32 v5, vcc, 0, v5, vcc
	global_atomic_add v1, v[4:5], v1, off offset:1024 sc0
	v_cvt_f32_u32_e32 v3, v0
	v_sub_u32_e32 v4, 0, v0
	v_rcp_iflag_f32_e32 v3, v3
	s_nop 0
	v_mul_f32_e32 v3, 0x4f7ffffe, v3
	v_cvt_u32_f32_e32 v3, v3
	v_mul_lo_u32 v4, v4, v3
	v_mul_hi_u32 v4, v3, v4
	v_add_u32_e32 v3, v3, v4
	s_waitcnt vmcnt(0)
	v_mul_hi_u32 v3, v1, v3
	v_mul_lo_u32 v5, v3, v0
	v_add_u32_e32 v4, 1, v1
	v_sub_u32_e32 v1, v1, v5
	v_add_u32_e32 v6, 1, v3
	v_cmp_ge_u32_e32 vcc, v1, v0
	v_sub_u32_e32 v5, v1, v0
	s_nop 0
	v_cndmask_b32_e32 v3, v3, v6, vcc
	v_cndmask_b32_e32 v1, v1, v5, vcc
	v_add_u32_e32 v5, 1, v3
	v_cmp_ge_u32_e32 vcc, v1, v0
	s_nop 1
	v_cndmask_b32_e32 v1, v3, v5, vcc
	v_mad_u64_u32 v[0:1], s[4:5], v0, v1, v[0:1]
	v_cmp_ne_u32_e32 vcc, v4, v0
	s_and_saveexec_b64 s[4:5], vcc
	s_xor_b64 s[4:5], exec, s[4:5]
	s_cbranch_execz .LBB0_589
	v_add_co_u32_e32 v0, vcc, 0x7000, v128
	s_nop 1
	v_addc_co_u32_e32 v1, vcc, 0, v129, vcc
	global_load_dword v0, v[0:1], off offset:1280 sc1
	s_waitcnt vmcnt(0)
	v_cmp_gt_u32_e32 vcc, 0x20, v0
	s_and_saveexec_b64 s[6:7], vcc
	s_cbranch_execz .LBB0_588
	s_mov_b64 s[8:9], 0x7500
	s_waitcnt lgkmcnt(0)
	v_lshl_add_u64 v[2:3], v[128:129], 0, s[8:9]
	s_mov_b64 s[8:9], 0x4200
	v_lshl_add_u64 v[0:1], v[128:129], 0, s[8:9]
	s_mov_b32 s24, 1
	s_mov_b64 s[8:9], 0
	s_branch .LBB0_580

.LBB0_584:
	s_andn2_b64 s[14:15], s[14:15], exec
	s_and_b64 s[20:21], s[20:21], exec
	s_or_b64 s[14:15], s[14:15], s[20:21]
	s_and_saveexec_b64 s[20:21], s[18:19]
	s_cbranch_execz .LBB0_579
	global_load_dword v4, v[2:3], off sc1
	s_add_i32 s24, s24, 1
	s_or_b64 s[14:15], s[14:15], exec
	s_waitcnt vmcnt(0)
	v_cmp_lt_u32_e32 vcc, 0x1f, v4
	s_orn2_b64 s[16:17], vcc, exec
	s_branch .LBB0_579

.LBB0_589:
	s_andn2_saveexec_b64 s[4:5], s[4:5]
	s_cbranch_execz .LBB0_605
	v_add_co_u32_e32 v0, vcc, 0x7000, v128
	buffer_wbl2 sc1
	s_waitcnt lgkmcnt(0)
	s_waitcnt vmcnt(0)
	v_addc_co_u32_e32 v1, vcc, 0, v129, vcc
	v_mov_b32_e32 v3, 1
	global_atomic_add v3, v[0:1], v3, off offset:1280 sc0
	v_cvt_f32_u32_e32 v0, v2
	v_sub_u32_e32 v4, 0, v2
	s_mov_b64 s[4:5], 0x7500
	s_mov_b64 s[6:7], 0
	v_rcp_iflag_f32_e32 v0, v0
	s_nop 0
	v_mul_f32_e32 v0, 0x4f7ffffe, v0
	v_cvt_u32_f32_e32 v5, v0
	v_lshl_add_u64 v[0:1], v[128:129], 0, s[4:5]
	v_mul_lo_u32 v4, v4, v5
	v_mul_hi_u32 v4, v5, v4
	v_add_u32_e32 v4, v5, v4
	s_waitcnt vmcnt(0)
	v_mul_hi_u32 v4, v3, v4
	v_mul_lo_u32 v6, v4, v2
	v_add_u32_e32 v5, 1, v3
	v_sub_u32_e32 v3, v3, v6
	v_add_u32_e32 v7, 1, v4
	v_cmp_ge_u32_e32 vcc, v3, v2
	v_sub_u32_e32 v6, v3, v2
	s_nop 0
	v_cndmask_b32_e32 v4, v4, v7, vcc
	v_cndmask_b32_e32 v3, v3, v6, vcc
	v_add_u32_e32 v6, 1, v4
	v_cmp_ge_u32_e32 vcc, v3, v2
	s_nop 1
	v_cndmask_b32_e32 v4, v4, v6, vcc
	v_mad_u64_u32 v[2:3], s[4:5], v2, v4, v[2:3]
	v_cmp_ne_u32_e32 vcc, v5, v2
	s_and_saveexec_b64 s[4:5], vcc
	s_cbranch_execz .LBB0_602
	global_load_dword v2, v[0:1], off sc1
	s_mov_b64 s[8:9], 0
	s_waitcnt vmcnt(0)
	v_cmp_gt_u32_e32 vcc, 0x20, v2
	s_and_saveexec_b64 s[6:7], vcc
	s_cbranch_execz .LBB0_601
	s_mov_b64 s[8:9], 0x4200
	v_lshl_add_u64 v[2:3], v[128:129], 0, s[8:9]
	s_mov_b32 s22, 1
	s_mov_b64 s[8:9], 0
	s_branch .LBB0_594

.LBB0_599:
	global_load_dword v5, v[0:1], off sc1
	s_add_i32 s22, s22, 1
	s_or_b64 s[14:15], s[14:15], exec
	s_waitcnt vmcnt(0)
	v_cmp_le_u32_e32 vcc, 0x20, v5
	s_orn2_b64 s[18:19], vcc, exec
	s_branch .LBB0_593

.LBB0_630:
	s_lshl_b32 s4, s3, 8
	s_mov_b32 s5, 0
	v_lshl_add_u64 v[4:5], v[130:131], 0, s[4:5]
	v_add_co_u32_e32 v4, vcc, 0x1000, v4
	v_mov_b32_e32 v1, 1
	s_nop 0
	v_addc_co_u32_e32 v5, vcc, 0, v5, vcc
	global_atomic_add v1, v[4:5], v1, off offset:1024 sc0
	v_cvt_f32_u32_e32 v3, v0
	v_sub_u32_e32 v4, 0, v0
	v_rcp_iflag_f32_e32 v3, v3
	s_nop 0
	v_mul_f32_e32 v3, 0x4f7ffffe, v3
	v_cvt_u32_f32_e32 v3, v3
	v_mul_lo_u32 v4, v4, v3
	v_mul_hi_u32 v4, v3, v4
	v_add_u32_e32 v3, v3, v4
	s_waitcnt vmcnt(0)
	v_mul_hi_u32 v3, v1, v3
	v_mul_lo_u32 v5, v3, v0
	v_add_u32_e32 v4, 1, v1
	v_sub_u32_e32 v1, v1, v5
	v_add_u32_e32 v6, 1, v3
	v_cmp_ge_u32_e32 vcc, v1, v0
	v_sub_u32_e32 v5, v1, v0
	s_nop 0
	v_cndmask_b32_e32 v3, v3, v6, vcc
	v_cndmask_b32_e32 v1, v1, v5, vcc
	v_add_u32_e32 v5, 1, v3
	v_cmp_ge_u32_e32 vcc, v1, v0
	s_nop 1
	v_cndmask_b32_e32 v1, v3, v5, vcc
	v_mad_u64_u32 v[0:1], s[4:5], v0, v1, v[0:1]
	v_cmp_ne_u32_e32 vcc, v4, v0
	s_and_saveexec_b64 s[4:5], vcc
	s_xor_b64 s[4:5], exec, s[4:5]
	s_cbranch_execz .LBB0_643
	v_add_co_u32_e32 v0, vcc, 0x7000, v128
	s_nop 1
	v_addc_co_u32_e32 v1, vcc, 0, v129, vcc
	global_load_dword v0, v[0:1], off offset:1280 sc1
	s_waitcnt vmcnt(0)
	v_cmp_gt_u32_e32 vcc, 0x28, v0
	s_and_saveexec_b64 s[6:7], vcc
	s_cbranch_execz .LBB0_642
	s_mov_b64 s[8:9], 0x7500
	s_waitcnt lgkmcnt(0)
	v_lshl_add_u64 v[2:3], v[128:129], 0, s[8:9]
	s_mov_b64 s[8:9], 0x4200
	v_lshl_add_u64 v[0:1], v[128:129], 0, s[8:9]
	s_mov_b32 s24, 1
	s_mov_b64 s[8:9], 0
	s_branch .LBB0_634

.LBB0_638:
	s_andn2_b64 s[14:15], s[14:15], exec
	s_and_b64 s[20:21], s[20:21], exec
	s_or_b64 s[14:15], s[14:15], s[20:21]
	s_and_saveexec_b64 s[20:21], s[18:19]
	s_cbranch_execz .LBB0_633
	global_load_dword v4, v[2:3], off sc1
	s_add_i32 s24, s24, 1
	s_or_b64 s[14:15], s[14:15], exec
	s_waitcnt vmcnt(0)
	v_cmp_lt_u32_e32 vcc, 0x27, v4
	s_orn2_b64 s[16:17], vcc, exec
	s_branch .LBB0_633

.LBB0_643:
	s_andn2_saveexec_b64 s[4:5], s[4:5]
	s_cbranch_execz .LBB0_659
	v_add_co_u32_e32 v0, vcc, 0x7000, v128
	buffer_wbl2 sc1
	s_waitcnt lgkmcnt(0)
	s_waitcnt vmcnt(0)
	v_addc_co_u32_e32 v1, vcc, 0, v129, vcc
	v_mov_b32_e32 v3, 1
	global_atomic_add v3, v[0:1], v3, off offset:1280 sc0
	v_cvt_f32_u32_e32 v0, v2
	v_sub_u32_e32 v4, 0, v2
	s_mov_b64 s[4:5], 0x7500
	s_mov_b64 s[6:7], 0
	v_rcp_iflag_f32_e32 v0, v0
	s_nop 0
	v_mul_f32_e32 v0, 0x4f7ffffe, v0
	v_cvt_u32_f32_e32 v5, v0
	v_lshl_add_u64 v[0:1], v[128:129], 0, s[4:5]
	v_mul_lo_u32 v4, v4, v5
	v_mul_hi_u32 v4, v5, v4
	v_add_u32_e32 v4, v5, v4
	s_waitcnt vmcnt(0)
	v_mul_hi_u32 v4, v3, v4
	v_mul_lo_u32 v6, v4, v2
	v_add_u32_e32 v5, 1, v3
	v_sub_u32_e32 v3, v3, v6
	v_add_u32_e32 v7, 1, v4
	v_cmp_ge_u32_e32 vcc, v3, v2
	v_sub_u32_e32 v6, v3, v2
	s_nop 0
	v_cndmask_b32_e32 v4, v4, v7, vcc
	v_cndmask_b32_e32 v3, v3, v6, vcc
	v_add_u32_e32 v6, 1, v4
	v_cmp_ge_u32_e32 vcc, v3, v2
	s_nop 1
	v_cndmask_b32_e32 v4, v4, v6, vcc
	v_mad_u64_u32 v[2:3], s[4:5], v2, v4, v[2:3]
	v_cmp_ne_u32_e32 vcc, v5, v2
	s_and_saveexec_b64 s[4:5], vcc
	s_cbranch_execz .LBB0_656
	global_load_dword v2, v[0:1], off sc1
	s_mov_b64 s[8:9], 0
	s_waitcnt vmcnt(0)
	v_cmp_gt_u32_e32 vcc, 0x28, v2
	s_and_saveexec_b64 s[6:7], vcc
	s_cbranch_execz .LBB0_655
	s_mov_b64 s[8:9], 0x4200
	v_lshl_add_u64 v[2:3], v[128:129], 0, s[8:9]
	s_mov_b32 s22, 1
	s_mov_b64 s[8:9], 0
	s_branch .LBB0_648

.LBB0_653:
	global_load_dword v5, v[0:1], off sc1
	s_add_i32 s22, s22, 1
	s_or_b64 s[14:15], s[14:15], exec
	s_waitcnt vmcnt(0)
	v_cmp_le_u32_e32 vcc, 0x28, v5
	s_orn2_b64 s[18:19], vcc, exec
	s_branch .LBB0_647

.LBB0_698:
	s_lshl_b32 s4, s3, 8
	s_mov_b32 s5, 0
	v_lshl_add_u64 v[4:5], v[130:131], 0, s[4:5]
	v_add_co_u32_e32 v4, vcc, 0x1000, v4
	v_mov_b32_e32 v1, 1
	s_nop 0
	v_addc_co_u32_e32 v5, vcc, 0, v5, vcc
	global_atomic_add v1, v[4:5], v1, off offset:1024 sc0
	v_cvt_f32_u32_e32 v3, v0
	v_sub_u32_e32 v4, 0, v0
	v_rcp_iflag_f32_e32 v3, v3
	s_nop 0
	v_mul_f32_e32 v3, 0x4f7ffffe, v3
	v_cvt_u32_f32_e32 v3, v3
	v_mul_lo_u32 v4, v4, v3
	v_mul_hi_u32 v4, v3, v4
	v_add_u32_e32 v3, v3, v4
	s_waitcnt vmcnt(0)
	v_mul_hi_u32 v3, v1, v3
	v_mul_lo_u32 v5, v3, v0
	v_add_u32_e32 v4, 1, v1
	v_sub_u32_e32 v1, v1, v5
	v_add_u32_e32 v6, 1, v3
	v_cmp_ge_u32_e32 vcc, v1, v0
	v_sub_u32_e32 v5, v1, v0
	s_nop 0
	v_cndmask_b32_e32 v3, v3, v6, vcc
	v_cndmask_b32_e32 v1, v1, v5, vcc
	v_add_u32_e32 v5, 1, v3
	v_cmp_ge_u32_e32 vcc, v1, v0
	s_nop 1
	v_cndmask_b32_e32 v1, v3, v5, vcc
	v_mad_u64_u32 v[0:1], s[4:5], v0, v1, v[0:1]
	v_cmp_ne_u32_e32 vcc, v4, v0
	s_and_saveexec_b64 s[4:5], vcc
	s_xor_b64 s[4:5], exec, s[4:5]
	s_cbranch_execz .LBB0_711
	v_add_co_u32_e32 v0, vcc, 0x7000, v128
	s_nop 1
	v_addc_co_u32_e32 v1, vcc, 0, v129, vcc
	global_load_dword v0, v[0:1], off offset:1280 sc1
	s_waitcnt vmcnt(0)
	v_cmp_gt_u32_e32 vcc, 0x30, v0
	s_and_saveexec_b64 s[6:7], vcc
	s_cbranch_execz .LBB0_710
	s_mov_b64 s[8:9], 0x7500
	s_waitcnt lgkmcnt(0)
	v_lshl_add_u64 v[2:3], v[128:129], 0, s[8:9]
	s_mov_b64 s[8:9], 0x4200
	v_lshl_add_u64 v[0:1], v[128:129], 0, s[8:9]
	s_mov_b32 s24, 1
	s_mov_b64 s[8:9], 0
	s_branch .LBB0_702

.LBB0_706:
	s_andn2_b64 s[14:15], s[14:15], exec
	s_and_b64 s[20:21], s[20:21], exec
	s_or_b64 s[14:15], s[14:15], s[20:21]
	s_and_saveexec_b64 s[20:21], s[18:19]
	s_cbranch_execz .LBB0_701
	global_load_dword v4, v[2:3], off sc1
	s_add_i32 s24, s24, 1
	s_or_b64 s[14:15], s[14:15], exec
	s_waitcnt vmcnt(0)
	v_cmp_lt_u32_e32 vcc, 0x2f, v4
	s_orn2_b64 s[16:17], vcc, exec
	s_branch .LBB0_701

.LBB0_711:
	s_andn2_saveexec_b64 s[4:5], s[4:5]
	s_cbranch_execz .LBB0_727
	v_add_co_u32_e32 v0, vcc, 0x7000, v128
	buffer_wbl2 sc1
	s_waitcnt lgkmcnt(0)
	s_waitcnt vmcnt(0)
	v_addc_co_u32_e32 v1, vcc, 0, v129, vcc
	v_mov_b32_e32 v3, 1
	global_atomic_add v3, v[0:1], v3, off offset:1280 sc0
	v_cvt_f32_u32_e32 v0, v2
	v_sub_u32_e32 v4, 0, v2
	s_mov_b64 s[4:5], 0x7500
	s_mov_b64 s[6:7], 0
	v_rcp_iflag_f32_e32 v0, v0
	s_nop 0
	v_mul_f32_e32 v0, 0x4f7ffffe, v0
	v_cvt_u32_f32_e32 v5, v0
	v_lshl_add_u64 v[0:1], v[128:129], 0, s[4:5]
	v_mul_lo_u32 v4, v4, v5
	v_mul_hi_u32 v4, v5, v4
	v_add_u32_e32 v4, v5, v4
	s_waitcnt vmcnt(0)
	v_mul_hi_u32 v4, v3, v4
	v_mul_lo_u32 v6, v4, v2
	v_add_u32_e32 v5, 1, v3
	v_sub_u32_e32 v3, v3, v6
	v_add_u32_e32 v7, 1, v4
	v_cmp_ge_u32_e32 vcc, v3, v2
	v_sub_u32_e32 v6, v3, v2
	s_nop 0
	v_cndmask_b32_e32 v4, v4, v7, vcc
	v_cndmask_b32_e32 v3, v3, v6, vcc
	v_add_u32_e32 v6, 1, v4
	v_cmp_ge_u32_e32 vcc, v3, v2
	s_nop 1
	v_cndmask_b32_e32 v4, v4, v6, vcc
	v_mad_u64_u32 v[2:3], s[4:5], v2, v4, v[2:3]
	v_cmp_ne_u32_e32 vcc, v5, v2
	s_and_saveexec_b64 s[4:5], vcc
	s_cbranch_execz .LBB0_724
	global_load_dword v2, v[0:1], off sc1
	s_mov_b64 s[8:9], 0
	s_waitcnt vmcnt(0)
	v_cmp_gt_u32_e32 vcc, 0x30, v2
	s_and_saveexec_b64 s[6:7], vcc
	s_cbranch_execz .LBB0_723
	s_mov_b64 s[8:9], 0x4200
	v_lshl_add_u64 v[2:3], v[128:129], 0, s[8:9]
	s_mov_b32 s22, 1
	s_mov_b64 s[8:9], 0
	s_branch .LBB0_716

.LBB0_721:
	global_load_dword v5, v[0:1], off sc1
	s_add_i32 s22, s22, 1
	s_or_b64 s[14:15], s[14:15], exec
	s_waitcnt vmcnt(0)
	v_cmp_le_u32_e32 vcc, 0x30, v5
	s_orn2_b64 s[18:19], vcc, exec
	s_branch .LBB0_715

.LBB0_760:
	s_lshl_b32 s4, s3, 8
	s_mov_b32 s5, 0
	v_lshl_add_u64 v[4:5], v[130:131], 0, s[4:5]
	v_add_co_u32_e32 v4, vcc, 0x1000, v4
	v_mov_b32_e32 v1, 1
	s_nop 0
	v_addc_co_u32_e32 v5, vcc, 0, v5, vcc
	global_atomic_add v1, v[4:5], v1, off offset:1024 sc0
	v_cvt_f32_u32_e32 v3, v0
	v_sub_u32_e32 v4, 0, v0
	v_rcp_iflag_f32_e32 v3, v3
	s_nop 0
	v_mul_f32_e32 v3, 0x4f7ffffe, v3
	v_cvt_u32_f32_e32 v3, v3
	v_mul_lo_u32 v4, v4, v3
	v_mul_hi_u32 v4, v3, v4
	v_add_u32_e32 v3, v3, v4
	s_waitcnt vmcnt(0)
	v_mul_hi_u32 v3, v1, v3
	v_mul_lo_u32 v5, v3, v0
	v_add_u32_e32 v4, 1, v1
	v_sub_u32_e32 v1, v1, v5
	v_add_u32_e32 v6, 1, v3
	v_cmp_ge_u32_e32 vcc, v1, v0
	v_sub_u32_e32 v5, v1, v0
	s_nop 0
	v_cndmask_b32_e32 v3, v3, v6, vcc
	v_cndmask_b32_e32 v1, v1, v5, vcc
	v_add_u32_e32 v5, 1, v3
	v_cmp_ge_u32_e32 vcc, v1, v0
	s_nop 1
	v_cndmask_b32_e32 v1, v3, v5, vcc
	v_mad_u64_u32 v[0:1], s[4:5], v0, v1, v[0:1]
	v_cmp_ne_u32_e32 vcc, v4, v0
	s_and_saveexec_b64 s[4:5], vcc
	s_xor_b64 s[4:5], exec, s[4:5]
	s_cbranch_execz .LBB0_773
	v_add_co_u32_e32 v0, vcc, 0x7000, v128
	s_nop 1
	v_addc_co_u32_e32 v1, vcc, 0, v129, vcc
	global_load_dword v0, v[0:1], off offset:1280 sc1
	s_waitcnt vmcnt(0)
	v_cmp_gt_u32_e32 vcc, 0x38, v0
	s_and_saveexec_b64 s[6:7], vcc
	s_cbranch_execz .LBB0_772
	s_mov_b64 s[8:9], 0x7500
	s_waitcnt lgkmcnt(0)
	v_lshl_add_u64 v[2:3], v[128:129], 0, s[8:9]
	s_mov_b64 s[8:9], 0x4200
	v_lshl_add_u64 v[0:1], v[128:129], 0, s[8:9]
	s_mov_b32 s24, 1
	s_mov_b64 s[8:9], 0
	s_branch .LBB0_764

.LBB0_768:
	s_andn2_b64 s[14:15], s[14:15], exec
	s_and_b64 s[20:21], s[20:21], exec
	s_or_b64 s[14:15], s[14:15], s[20:21]
	s_and_saveexec_b64 s[20:21], s[18:19]
	s_cbranch_execz .LBB0_763
	global_load_dword v4, v[2:3], off sc1
	s_add_i32 s24, s24, 1
	s_or_b64 s[14:15], s[14:15], exec
	s_waitcnt vmcnt(0)
	v_cmp_lt_u32_e32 vcc, 0x37, v4
	s_orn2_b64 s[16:17], vcc, exec
	s_branch .LBB0_763

.LBB0_773:
	s_andn2_saveexec_b64 s[4:5], s[4:5]
	s_cbranch_execz .LBB0_789
	v_add_co_u32_e32 v0, vcc, 0x7000, v128
	buffer_wbl2 sc1
	s_waitcnt lgkmcnt(0)
	s_waitcnt vmcnt(0)
	v_addc_co_u32_e32 v1, vcc, 0, v129, vcc
	v_mov_b32_e32 v3, 1
	global_atomic_add v3, v[0:1], v3, off offset:1280 sc0
	v_cvt_f32_u32_e32 v0, v2
	v_sub_u32_e32 v4, 0, v2
	s_mov_b64 s[4:5], 0x7500
	s_mov_b64 s[6:7], 0
	v_rcp_iflag_f32_e32 v0, v0
	s_nop 0
	v_mul_f32_e32 v0, 0x4f7ffffe, v0
	v_cvt_u32_f32_e32 v5, v0
	v_lshl_add_u64 v[0:1], v[128:129], 0, s[4:5]
	v_mul_lo_u32 v4, v4, v5
	v_mul_hi_u32 v4, v5, v4
	v_add_u32_e32 v4, v5, v4
	s_waitcnt vmcnt(0)
	v_mul_hi_u32 v4, v3, v4
	v_mul_lo_u32 v6, v4, v2
	v_add_u32_e32 v5, 1, v3
	v_sub_u32_e32 v3, v3, v6
	v_add_u32_e32 v7, 1, v4
	v_cmp_ge_u32_e32 vcc, v3, v2
	v_sub_u32_e32 v6, v3, v2
	s_nop 0
	v_cndmask_b32_e32 v4, v4, v7, vcc
	v_cndmask_b32_e32 v3, v3, v6, vcc
	v_add_u32_e32 v6, 1, v4
	v_cmp_ge_u32_e32 vcc, v3, v2
	s_nop 1
	v_cndmask_b32_e32 v4, v4, v6, vcc
	v_mad_u64_u32 v[2:3], s[4:5], v2, v4, v[2:3]
	v_cmp_ne_u32_e32 vcc, v5, v2
	s_and_saveexec_b64 s[4:5], vcc
	s_cbranch_execz .LBB0_786
	global_load_dword v2, v[0:1], off sc1
	s_mov_b64 s[8:9], 0
	s_waitcnt vmcnt(0)
	v_cmp_gt_u32_e32 vcc, 0x38, v2
	s_and_saveexec_b64 s[6:7], vcc
	s_cbranch_execz .LBB0_785
	s_mov_b64 s[8:9], 0x4200
	v_lshl_add_u64 v[2:3], v[128:129], 0, s[8:9]
	s_mov_b32 s22, 1
	s_mov_b64 s[8:9], 0
	s_branch .LBB0_778

.LBB0_783:
	global_load_dword v5, v[0:1], off sc1
	s_add_i32 s22, s22, 1
	s_or_b64 s[14:15], s[14:15], exec
	s_waitcnt vmcnt(0)
	v_cmp_le_u32_e32 vcc, 0x38, v5
	s_orn2_b64 s[18:19], vcc, exec
	s_branch .LBB0_777

.LBB0_820:
	s_lshl_b32 s4, s3, 8
	s_mov_b32 s5, 0
	v_lshl_add_u64 v[4:5], v[130:131], 0, s[4:5]
	v_add_co_u32_e32 v4, vcc, 0x1000, v4
	v_mov_b32_e32 v1, 1
	s_nop 0
	v_addc_co_u32_e32 v5, vcc, 0, v5, vcc
	global_atomic_add v1, v[4:5], v1, off offset:1024 sc0
	v_cvt_f32_u32_e32 v3, v0
	v_sub_u32_e32 v4, 0, v0
	v_rcp_iflag_f32_e32 v3, v3
	s_nop 0
	v_mul_f32_e32 v3, 0x4f7ffffe, v3
	v_cvt_u32_f32_e32 v3, v3
	v_mul_lo_u32 v4, v4, v3
	v_mul_hi_u32 v4, v3, v4
	v_add_u32_e32 v3, v3, v4
	s_waitcnt vmcnt(0)
	v_mul_hi_u32 v3, v1, v3
	v_mul_lo_u32 v5, v3, v0
	v_add_u32_e32 v4, 1, v1
	v_sub_u32_e32 v1, v1, v5
	v_add_u32_e32 v6, 1, v3
	v_cmp_ge_u32_e32 vcc, v1, v0
	v_sub_u32_e32 v5, v1, v0
	s_nop 0
	v_cndmask_b32_e32 v3, v3, v6, vcc
	v_cndmask_b32_e32 v1, v1, v5, vcc
	v_add_u32_e32 v5, 1, v3
	v_cmp_ge_u32_e32 vcc, v1, v0
	s_nop 1
	v_cndmask_b32_e32 v1, v3, v5, vcc
	v_mad_u64_u32 v[0:1], s[4:5], v0, v1, v[0:1]
	v_cmp_ne_u32_e32 vcc, v4, v0
	s_and_saveexec_b64 s[4:5], vcc
	s_xor_b64 s[4:5], exec, s[4:5]
	s_cbranch_execz .LBB0_833
	v_add_co_u32_e32 v0, vcc, 0x7000, v128
	s_nop 1
	v_addc_co_u32_e32 v1, vcc, 0, v129, vcc
	global_load_dword v0, v[0:1], off offset:1280 sc1
	s_waitcnt vmcnt(0)
	v_cmp_gt_u32_e32 vcc, 0x40, v0
	s_and_saveexec_b64 s[6:7], vcc
	s_cbranch_execz .LBB0_832
	s_mov_b64 s[8:9], 0x7500
	s_waitcnt lgkmcnt(0)
	v_lshl_add_u64 v[2:3], v[128:129], 0, s[8:9]
	s_mov_b64 s[8:9], 0x4200
	v_lshl_add_u64 v[0:1], v[128:129], 0, s[8:9]
	s_mov_b32 s24, 1
	s_mov_b64 s[8:9], 0
	s_branch .LBB0_824

.LBB0_828:
	s_andn2_b64 s[14:15], s[14:15], exec
	s_and_b64 s[20:21], s[20:21], exec
	s_or_b64 s[14:15], s[14:15], s[20:21]
	s_and_saveexec_b64 s[20:21], s[18:19]
	s_cbranch_execz .LBB0_823
	global_load_dword v4, v[2:3], off sc1
	s_add_i32 s24, s24, 1
	s_or_b64 s[14:15], s[14:15], exec
	s_waitcnt vmcnt(0)
	v_cmp_lt_u32_e32 vcc, 0x3f, v4
	s_orn2_b64 s[16:17], vcc, exec
	s_branch .LBB0_823

.LBB0_833:
	s_andn2_saveexec_b64 s[4:5], s[4:5]
	s_cbranch_execz .LBB0_849
	v_add_co_u32_e32 v0, vcc, 0x7000, v128
	buffer_wbl2 sc1
	s_waitcnt lgkmcnt(0)
	s_waitcnt vmcnt(0)
	v_addc_co_u32_e32 v1, vcc, 0, v129, vcc
	v_mov_b32_e32 v3, 1
	global_atomic_add v3, v[0:1], v3, off offset:1280 sc0
	v_cvt_f32_u32_e32 v0, v2
	v_sub_u32_e32 v4, 0, v2
	s_mov_b64 s[4:5], 0x7500
	s_mov_b64 s[6:7], 0
	v_rcp_iflag_f32_e32 v0, v0
	s_nop 0
	v_mul_f32_e32 v0, 0x4f7ffffe, v0
	v_cvt_u32_f32_e32 v5, v0
	v_lshl_add_u64 v[0:1], v[128:129], 0, s[4:5]
	v_mul_lo_u32 v4, v4, v5
	v_mul_hi_u32 v4, v5, v4
	v_add_u32_e32 v4, v5, v4
	s_waitcnt vmcnt(0)
	v_mul_hi_u32 v4, v3, v4
	v_mul_lo_u32 v6, v4, v2
	v_add_u32_e32 v5, 1, v3
	v_sub_u32_e32 v3, v3, v6
	v_add_u32_e32 v7, 1, v4
	v_cmp_ge_u32_e32 vcc, v3, v2
	v_sub_u32_e32 v6, v3, v2
	s_nop 0
	v_cndmask_b32_e32 v4, v4, v7, vcc
	v_cndmask_b32_e32 v3, v3, v6, vcc
	v_add_u32_e32 v6, 1, v4
	v_cmp_ge_u32_e32 vcc, v3, v2
	s_nop 1
	v_cndmask_b32_e32 v4, v4, v6, vcc
	v_mad_u64_u32 v[2:3], s[4:5], v2, v4, v[2:3]
	v_cmp_ne_u32_e32 vcc, v5, v2
	s_and_saveexec_b64 s[4:5], vcc
	s_cbranch_execz .LBB0_846
	global_load_dword v2, v[0:1], off sc1
	s_mov_b64 s[8:9], 0
	s_waitcnt vmcnt(0)
	v_cmp_gt_u32_e32 vcc, 0x40, v2
	s_and_saveexec_b64 s[6:7], vcc
	s_cbranch_execz .LBB0_845
	s_mov_b64 s[8:9], 0x4200
	v_lshl_add_u64 v[2:3], v[128:129], 0, s[8:9]
	s_mov_b32 s22, 1
	s_mov_b64 s[8:9], 0
	s_branch .LBB0_838

.LBB0_843:
	global_load_dword v5, v[0:1], off sc1
	s_add_i32 s22, s22, 1
	s_or_b64 s[14:15], s[14:15], exec
	s_waitcnt vmcnt(0)
	v_cmp_le_u32_e32 vcc, 0x40, v5
	s_orn2_b64 s[18:19], vcc, exec
	s_branch .LBB0_837

.LBB0_892:
	s_lshl_b32 s4, s3, 8
	s_mov_b32 s5, 0
	v_lshl_add_u64 v[4:5], v[130:131], 0, s[4:5]
	v_add_co_u32_e32 v4, vcc, 0x1000, v4
	v_mov_b32_e32 v1, 1
	s_nop 0
	v_addc_co_u32_e32 v5, vcc, 0, v5, vcc
	global_atomic_add v1, v[4:5], v1, off offset:1024 sc0
	v_cvt_f32_u32_e32 v3, v0
	v_sub_u32_e32 v4, 0, v0
	v_rcp_iflag_f32_e32 v3, v3
	s_nop 0
	v_mul_f32_e32 v3, 0x4f7ffffe, v3
	v_cvt_u32_f32_e32 v3, v3
	v_mul_lo_u32 v4, v4, v3
	v_mul_hi_u32 v4, v3, v4
	v_add_u32_e32 v3, v3, v4
	s_waitcnt vmcnt(0)
	v_mul_hi_u32 v3, v1, v3
	v_mul_lo_u32 v5, v3, v0
	v_add_u32_e32 v4, 1, v1
	v_sub_u32_e32 v1, v1, v5
	v_add_u32_e32 v6, 1, v3
	v_cmp_ge_u32_e32 vcc, v1, v0
	v_sub_u32_e32 v5, v1, v0
	s_nop 0
	v_cndmask_b32_e32 v3, v3, v6, vcc
	v_cndmask_b32_e32 v1, v1, v5, vcc
	v_add_u32_e32 v5, 1, v3
	v_cmp_ge_u32_e32 vcc, v1, v0
	s_nop 1
	v_cndmask_b32_e32 v1, v3, v5, vcc
	v_mad_u64_u32 v[0:1], s[4:5], v0, v1, v[0:1]
	v_cmp_ne_u32_e32 vcc, v4, v0
	s_and_saveexec_b64 s[4:5], vcc
	s_xor_b64 s[4:5], exec, s[4:5]
	s_cbranch_execz .LBB0_905
	v_add_co_u32_e32 v0, vcc, 0x7000, v128
	s_nop 1
	v_addc_co_u32_e32 v1, vcc, 0, v129, vcc
	global_load_dword v0, v[0:1], off offset:1280 sc1
	s_waitcnt vmcnt(0)
	v_cmp_gt_u32_e32 vcc, 0x48, v0
	s_and_saveexec_b64 s[6:7], vcc
	s_cbranch_execz .LBB0_904
	s_mov_b64 s[8:9], 0x7500
	s_waitcnt lgkmcnt(0)
	v_lshl_add_u64 v[2:3], v[128:129], 0, s[8:9]
	s_mov_b64 s[8:9], 0x4200
	v_lshl_add_u64 v[0:1], v[128:129], 0, s[8:9]
	s_mov_b32 s24, 1
	s_mov_b64 s[8:9], 0
	s_branch .LBB0_896

.LBB0_900:
	s_andn2_b64 s[14:15], s[14:15], exec
	s_and_b64 s[20:21], s[20:21], exec
	s_or_b64 s[14:15], s[14:15], s[20:21]
	s_and_saveexec_b64 s[20:21], s[18:19]
	s_cbranch_execz .LBB0_895
	global_load_dword v4, v[2:3], off sc1
	s_add_i32 s24, s24, 1
	s_or_b64 s[14:15], s[14:15], exec
	s_waitcnt vmcnt(0)
	v_cmp_lt_u32_e32 vcc, 0x47, v4
	s_orn2_b64 s[16:17], vcc, exec
	s_branch .LBB0_895

.LBB0_905:
	s_andn2_saveexec_b64 s[4:5], s[4:5]
	s_cbranch_execz .LBB0_921
	v_add_co_u32_e32 v0, vcc, 0x7000, v128
	buffer_wbl2 sc1
	s_waitcnt lgkmcnt(0)
	s_waitcnt vmcnt(0)
	v_addc_co_u32_e32 v1, vcc, 0, v129, vcc
	v_mov_b32_e32 v3, 1
	global_atomic_add v3, v[0:1], v3, off offset:1280 sc0
	v_cvt_f32_u32_e32 v0, v2
	v_sub_u32_e32 v4, 0, v2
	s_mov_b64 s[4:5], 0x7500
	s_mov_b64 s[6:7], 0
	v_rcp_iflag_f32_e32 v0, v0
	s_nop 0
	v_mul_f32_e32 v0, 0x4f7ffffe, v0
	v_cvt_u32_f32_e32 v5, v0
	v_lshl_add_u64 v[0:1], v[128:129], 0, s[4:5]
	v_mul_lo_u32 v4, v4, v5
	v_mul_hi_u32 v4, v5, v4
	v_add_u32_e32 v4, v5, v4
	s_waitcnt vmcnt(0)
	v_mul_hi_u32 v4, v3, v4
	v_mul_lo_u32 v6, v4, v2
	v_add_u32_e32 v5, 1, v3
	v_sub_u32_e32 v3, v3, v6
	v_add_u32_e32 v7, 1, v4
	v_cmp_ge_u32_e32 vcc, v3, v2
	v_sub_u32_e32 v6, v3, v2
	s_nop 0
	v_cndmask_b32_e32 v4, v4, v7, vcc
	v_cndmask_b32_e32 v3, v3, v6, vcc
	v_add_u32_e32 v6, 1, v4
	v_cmp_ge_u32_e32 vcc, v3, v2
	s_nop 1
	v_cndmask_b32_e32 v4, v4, v6, vcc
	v_mad_u64_u32 v[2:3], s[4:5], v2, v4, v[2:3]
	v_cmp_ne_u32_e32 vcc, v5, v2
	s_and_saveexec_b64 s[4:5], vcc
	s_cbranch_execz .LBB0_918
	global_load_dword v2, v[0:1], off sc1
	s_mov_b64 s[8:9], 0
	s_waitcnt vmcnt(0)
	v_cmp_gt_u32_e32 vcc, 0x48, v2
	s_and_saveexec_b64 s[6:7], vcc
	s_cbranch_execz .LBB0_917
	s_mov_b64 s[8:9], 0x4200
	v_lshl_add_u64 v[2:3], v[128:129], 0, s[8:9]
	s_mov_b32 s22, 1
	s_mov_b64 s[8:9], 0
	s_branch .LBB0_910

.LBB0_915:
	global_load_dword v5, v[0:1], off sc1
	s_add_i32 s22, s22, 1
	s_or_b64 s[14:15], s[14:15], exec
	s_waitcnt vmcnt(0)
	v_cmp_le_u32_e32 vcc, 0x48, v5
	s_orn2_b64 s[18:19], vcc, exec
	s_branch .LBB0_909

.LBB0_942:
	s_lshl_b32 s4, s3, 8
	s_mov_b32 s5, 0
	v_lshl_add_u64 v[4:5], v[130:131], 0, s[4:5]
	v_add_co_u32_e32 v4, vcc, 0x1000, v4
	v_mov_b32_e32 v1, 1
	s_nop 0
	v_addc_co_u32_e32 v5, vcc, 0, v5, vcc
	global_atomic_add v1, v[4:5], v1, off offset:1024 sc0
	v_cvt_f32_u32_e32 v3, v0
	v_sub_u32_e32 v4, 0, v0
	v_rcp_iflag_f32_e32 v3, v3
	s_nop 0
	v_mul_f32_e32 v3, 0x4f7ffffe, v3
	v_cvt_u32_f32_e32 v3, v3
	v_mul_lo_u32 v4, v4, v3
	v_mul_hi_u32 v4, v3, v4
	v_add_u32_e32 v3, v3, v4
	s_waitcnt vmcnt(0)
	v_mul_hi_u32 v3, v1, v3
	v_mul_lo_u32 v5, v3, v0
	v_add_u32_e32 v4, 1, v1
	v_sub_u32_e32 v1, v1, v5
	v_add_u32_e32 v6, 1, v3
	v_cmp_ge_u32_e32 vcc, v1, v0
	v_sub_u32_e32 v5, v1, v0
	s_nop 0
	v_cndmask_b32_e32 v3, v3, v6, vcc
	v_cndmask_b32_e32 v1, v1, v5, vcc
	v_add_u32_e32 v5, 1, v3
	v_cmp_ge_u32_e32 vcc, v1, v0
	s_nop 1
	v_cndmask_b32_e32 v1, v3, v5, vcc
	v_mad_u64_u32 v[0:1], s[4:5], v0, v1, v[0:1]
	v_cmp_ne_u32_e32 vcc, v4, v0
	s_and_saveexec_b64 s[4:5], vcc
	s_xor_b64 s[4:5], exec, s[4:5]
	s_cbranch_execz .LBB0_955
	v_add_co_u32_e32 v0, vcc, 0x7000, v128
	s_nop 1
	v_addc_co_u32_e32 v1, vcc, 0, v129, vcc
	global_load_dword v0, v[0:1], off offset:1280 sc1
	s_waitcnt vmcnt(0)
	v_cmp_gt_u32_e32 vcc, 0x50, v0
	s_and_saveexec_b64 s[6:7], vcc
	s_cbranch_execz .LBB0_954
	s_mov_b64 s[8:9], 0x7500
	s_waitcnt lgkmcnt(0)
	v_lshl_add_u64 v[2:3], v[128:129], 0, s[8:9]
	s_mov_b64 s[8:9], 0x4200
	v_lshl_add_u64 v[0:1], v[128:129], 0, s[8:9]
	s_mov_b32 s24, 1
	s_mov_b64 s[8:9], 0
	s_branch .LBB0_946

.LBB0_950:
	s_andn2_b64 s[14:15], s[14:15], exec
	s_and_b64 s[20:21], s[20:21], exec
	s_or_b64 s[14:15], s[14:15], s[20:21]
	s_and_saveexec_b64 s[20:21], s[18:19]
	s_cbranch_execz .LBB0_945
	global_load_dword v4, v[2:3], off sc1
	s_add_i32 s24, s24, 1
	s_or_b64 s[14:15], s[14:15], exec
	s_waitcnt vmcnt(0)
	v_cmp_lt_u32_e32 vcc, 0x4f, v4
	s_orn2_b64 s[16:17], vcc, exec
	s_branch .LBB0_945

.LBB0_955:
	s_andn2_saveexec_b64 s[4:5], s[4:5]
	s_cbranch_execz .LBB0_971
	v_add_co_u32_e32 v0, vcc, 0x7000, v128
	buffer_wbl2 sc1
	s_waitcnt lgkmcnt(0)
	s_waitcnt vmcnt(0)
	v_addc_co_u32_e32 v1, vcc, 0, v129, vcc
	v_mov_b32_e32 v3, 1
	global_atomic_add v3, v[0:1], v3, off offset:1280 sc0
	v_cvt_f32_u32_e32 v0, v2
	v_sub_u32_e32 v4, 0, v2
	s_mov_b64 s[4:5], 0x7500
	s_mov_b64 s[6:7], 0
	v_rcp_iflag_f32_e32 v0, v0
	s_nop 0
	v_mul_f32_e32 v0, 0x4f7ffffe, v0
	v_cvt_u32_f32_e32 v5, v0
	v_lshl_add_u64 v[0:1], v[128:129], 0, s[4:5]
	v_mul_lo_u32 v4, v4, v5
	v_mul_hi_u32 v4, v5, v4
	v_add_u32_e32 v4, v5, v4
	s_waitcnt vmcnt(0)
	v_mul_hi_u32 v4, v3, v4
	v_mul_lo_u32 v6, v4, v2
	v_add_u32_e32 v5, 1, v3
	v_sub_u32_e32 v3, v3, v6
	v_add_u32_e32 v7, 1, v4
	v_cmp_ge_u32_e32 vcc, v3, v2
	v_sub_u32_e32 v6, v3, v2
	s_nop 0
	v_cndmask_b32_e32 v4, v4, v7, vcc
	v_cndmask_b32_e32 v3, v3, v6, vcc
	v_add_u32_e32 v6, 1, v4
	v_cmp_ge_u32_e32 vcc, v3, v2
	s_nop 1
	v_cndmask_b32_e32 v4, v4, v6, vcc
	v_mad_u64_u32 v[2:3], s[4:5], v2, v4, v[2:3]
	v_cmp_ne_u32_e32 vcc, v5, v2
	s_and_saveexec_b64 s[4:5], vcc
	s_cbranch_execz .LBB0_968
	global_load_dword v2, v[0:1], off sc1
	s_mov_b64 s[8:9], 0
	s_waitcnt vmcnt(0)
	v_cmp_gt_u32_e32 vcc, 0x50, v2
	s_and_saveexec_b64 s[6:7], vcc
	s_cbranch_execz .LBB0_967
	s_mov_b64 s[8:9], 0x4200
	v_lshl_add_u64 v[2:3], v[128:129], 0, s[8:9]
	s_mov_b32 s22, 1
	s_mov_b64 s[8:9], 0
	s_branch .LBB0_960

.LBB0_965:
	global_load_dword v5, v[0:1], off sc1
	s_add_i32 s22, s22, 1
	s_or_b64 s[14:15], s[14:15], exec
	s_waitcnt vmcnt(0)
	v_cmp_le_u32_e32 vcc, 0x50, v5
	s_orn2_b64 s[18:19], vcc, exec
	s_branch .LBB0_959

.LBB0_1010:
	s_lshl_b32 s4, s3, 8
	s_mov_b32 s5, 0
	v_lshl_add_u64 v[4:5], v[130:131], 0, s[4:5]
	v_add_co_u32_e32 v4, vcc, 0x1000, v4
	v_mov_b32_e32 v1, 1
	s_nop 0
	v_addc_co_u32_e32 v5, vcc, 0, v5, vcc
	global_atomic_add v1, v[4:5], v1, off offset:1024 sc0
	v_cvt_f32_u32_e32 v3, v0
	v_sub_u32_e32 v4, 0, v0
	v_rcp_iflag_f32_e32 v3, v3
	s_nop 0
	v_mul_f32_e32 v3, 0x4f7ffffe, v3
	v_cvt_u32_f32_e32 v3, v3
	v_mul_lo_u32 v4, v4, v3
	v_mul_hi_u32 v4, v3, v4
	v_add_u32_e32 v3, v3, v4
	s_waitcnt vmcnt(0)
	v_mul_hi_u32 v3, v1, v3
	v_mul_lo_u32 v5, v3, v0
	v_add_u32_e32 v4, 1, v1
	v_sub_u32_e32 v1, v1, v5
	v_add_u32_e32 v6, 1, v3
	v_cmp_ge_u32_e32 vcc, v1, v0
	v_sub_u32_e32 v5, v1, v0
	s_nop 0
	v_cndmask_b32_e32 v3, v3, v6, vcc
	v_cndmask_b32_e32 v1, v1, v5, vcc
	v_add_u32_e32 v5, 1, v3
	v_cmp_ge_u32_e32 vcc, v1, v0
	s_nop 1
	v_cndmask_b32_e32 v1, v3, v5, vcc
	v_mad_u64_u32 v[0:1], s[4:5], v0, v1, v[0:1]
	v_cmp_ne_u32_e32 vcc, v4, v0
	s_and_saveexec_b64 s[4:5], vcc
	s_xor_b64 s[4:5], exec, s[4:5]
	s_cbranch_execz .LBB0_1023
	v_add_co_u32_e32 v0, vcc, 0x7000, v128
	s_nop 1
	v_addc_co_u32_e32 v1, vcc, 0, v129, vcc
	global_load_dword v0, v[0:1], off offset:1280 sc1
	s_waitcnt vmcnt(0)
	v_cmp_gt_u32_e32 vcc, 0x58, v0
	s_and_saveexec_b64 s[6:7], vcc
	s_cbranch_execz .LBB0_1022
	s_mov_b64 s[8:9], 0x7500
	s_waitcnt lgkmcnt(0)
	v_lshl_add_u64 v[2:3], v[128:129], 0, s[8:9]
	s_mov_b64 s[8:9], 0x4200
	v_lshl_add_u64 v[0:1], v[128:129], 0, s[8:9]
	s_mov_b32 s24, 1
	s_mov_b64 s[8:9], 0
	s_branch .LBB0_1014

.LBB0_1018:
	s_andn2_b64 s[14:15], s[14:15], exec
	s_and_b64 s[20:21], s[20:21], exec
	s_or_b64 s[14:15], s[14:15], s[20:21]
	s_and_saveexec_b64 s[20:21], s[18:19]
	s_cbranch_execz .LBB0_1013
	global_load_dword v4, v[2:3], off sc1
	s_add_i32 s24, s24, 1
	s_or_b64 s[14:15], s[14:15], exec
	s_waitcnt vmcnt(0)
	v_cmp_lt_u32_e32 vcc, 0x57, v4
	s_orn2_b64 s[16:17], vcc, exec
	s_branch .LBB0_1013

.LBB0_1023:
	s_andn2_saveexec_b64 s[4:5], s[4:5]
	s_cbranch_execz .LBB0_1039
	v_add_co_u32_e32 v0, vcc, 0x7000, v128
	buffer_wbl2 sc1
	s_waitcnt lgkmcnt(0)
	s_waitcnt vmcnt(0)
	v_addc_co_u32_e32 v1, vcc, 0, v129, vcc
	v_mov_b32_e32 v3, 1
	global_atomic_add v3, v[0:1], v3, off offset:1280 sc0
	v_cvt_f32_u32_e32 v0, v2
	v_sub_u32_e32 v4, 0, v2
	s_mov_b64 s[4:5], 0x7500
	s_mov_b64 s[6:7], 0
	v_rcp_iflag_f32_e32 v0, v0
	s_nop 0
	v_mul_f32_e32 v0, 0x4f7ffffe, v0
	v_cvt_u32_f32_e32 v5, v0
	v_lshl_add_u64 v[0:1], v[128:129], 0, s[4:5]
	v_mul_lo_u32 v4, v4, v5
	v_mul_hi_u32 v4, v5, v4
	v_add_u32_e32 v4, v5, v4
	s_waitcnt vmcnt(0)
	v_mul_hi_u32 v4, v3, v4
	v_mul_lo_u32 v6, v4, v2
	v_add_u32_e32 v5, 1, v3
	v_sub_u32_e32 v3, v3, v6
	v_add_u32_e32 v7, 1, v4
	v_cmp_ge_u32_e32 vcc, v3, v2
	v_sub_u32_e32 v6, v3, v2
	s_nop 0
	v_cndmask_b32_e32 v4, v4, v7, vcc
	v_cndmask_b32_e32 v3, v3, v6, vcc
	v_add_u32_e32 v6, 1, v4
	v_cmp_ge_u32_e32 vcc, v3, v2
	s_nop 1
	v_cndmask_b32_e32 v4, v4, v6, vcc
	v_mad_u64_u32 v[2:3], s[4:5], v2, v4, v[2:3]
	v_cmp_ne_u32_e32 vcc, v5, v2
	s_and_saveexec_b64 s[4:5], vcc
	s_cbranch_execz .LBB0_1036
	global_load_dword v2, v[0:1], off sc1
	s_mov_b64 s[8:9], 0
	s_waitcnt vmcnt(0)
	v_cmp_gt_u32_e32 vcc, 0x58, v2
	s_and_saveexec_b64 s[6:7], vcc
	s_cbranch_execz .LBB0_1035
	s_mov_b64 s[8:9], 0x4200
	v_lshl_add_u64 v[2:3], v[128:129], 0, s[8:9]
	s_mov_b32 s22, 1
	s_mov_b64 s[8:9], 0
	s_branch .LBB0_1028

.LBB0_1033:
	global_load_dword v5, v[0:1], off sc1
	s_add_i32 s22, s22, 1
	s_or_b64 s[14:15], s[14:15], exec
	s_waitcnt vmcnt(0)
	v_cmp_le_u32_e32 vcc, 0x58, v5
	s_orn2_b64 s[18:19], vcc, exec
	s_branch .LBB0_1027

.LBB0_1224:
	s_lshl_b32 s4, s3, 8
	s_mov_b32 s5, 0
	v_lshl_add_u64 v[4:5], v[130:131], 0, s[4:5]
	v_add_co_u32_e32 v4, vcc, 0x1000, v4
	v_mov_b32_e32 v1, 1
	s_nop 0
	v_addc_co_u32_e32 v5, vcc, 0, v5, vcc
	global_atomic_add v1, v[4:5], v1, off offset:1024 sc0
	v_cvt_f32_u32_e32 v3, v0
	v_sub_u32_e32 v4, 0, v0
	v_rcp_iflag_f32_e32 v3, v3
	s_nop 0
	v_mul_f32_e32 v3, 0x4f7ffffe, v3
	v_cvt_u32_f32_e32 v3, v3
	v_mul_lo_u32 v4, v4, v3
	v_mul_hi_u32 v4, v3, v4
	v_add_u32_e32 v3, v3, v4
	s_waitcnt vmcnt(0)
	v_mul_hi_u32 v3, v1, v3
	v_mul_lo_u32 v5, v3, v0
	v_add_u32_e32 v4, 1, v1
	v_sub_u32_e32 v1, v1, v5
	v_add_u32_e32 v6, 1, v3
	v_cmp_ge_u32_e32 vcc, v1, v0
	v_sub_u32_e32 v5, v1, v0
	s_nop 0
	v_cndmask_b32_e32 v3, v3, v6, vcc
	v_cndmask_b32_e32 v1, v1, v5, vcc
	v_add_u32_e32 v5, 1, v3
	v_cmp_ge_u32_e32 vcc, v1, v0
	s_nop 1
	v_cndmask_b32_e32 v1, v3, v5, vcc
	v_mad_u64_u32 v[0:1], s[4:5], v0, v1, v[0:1]
	v_cmp_ne_u32_e32 vcc, v4, v0
	s_and_saveexec_b64 s[4:5], vcc
	s_xor_b64 s[4:5], exec, s[4:5]
	s_cbranch_execz .LBB0_1237
	v_add_co_u32_e32 v0, vcc, 0x7000, v128
	s_nop 1
	v_addc_co_u32_e32 v1, vcc, 0, v129, vcc
	global_load_dword v0, v[0:1], off offset:1280 sc1
	s_waitcnt vmcnt(0)
	v_cmp_gt_u32_e32 vcc, 0x60, v0
	s_and_saveexec_b64 s[6:7], vcc
	s_cbranch_execz .LBB0_1236
	s_mov_b64 s[8:9], 0x7500
	s_waitcnt lgkmcnt(0)
	v_lshl_add_u64 v[2:3], v[128:129], 0, s[8:9]
	s_mov_b64 s[8:9], 0x4200
	v_lshl_add_u64 v[0:1], v[128:129], 0, s[8:9]
	s_mov_b32 s24, 1
	s_mov_b64 s[8:9], 0
	s_branch .LBB0_1228

.LBB0_1232:
	s_andn2_b64 s[14:15], s[14:15], exec
	s_and_b64 s[20:21], s[20:21], exec
	s_or_b64 s[14:15], s[14:15], s[20:21]
	s_and_saveexec_b64 s[20:21], s[18:19]
	s_cbranch_execz .LBB0_1227
	global_load_dword v4, v[2:3], off sc1
	s_add_i32 s24, s24, 1
	s_or_b64 s[14:15], s[14:15], exec
	s_waitcnt vmcnt(0)
	v_cmp_lt_u32_e32 vcc, 0x5f, v4
	s_orn2_b64 s[16:17], vcc, exec
	s_branch .LBB0_1227

.LBB0_1237:
	s_andn2_saveexec_b64 s[4:5], s[4:5]
	s_cbranch_execz .LBB0_1253
	v_add_co_u32_e32 v0, vcc, 0x7000, v128
	buffer_wbl2 sc1
	s_waitcnt lgkmcnt(0)
	s_waitcnt vmcnt(0)
	v_addc_co_u32_e32 v1, vcc, 0, v129, vcc
	v_mov_b32_e32 v3, 1
	global_atomic_add v3, v[0:1], v3, off offset:1280 sc0
	v_cvt_f32_u32_e32 v0, v2
	v_sub_u32_e32 v4, 0, v2
	s_mov_b64 s[4:5], 0x7500
	s_mov_b64 s[6:7], 0
	v_rcp_iflag_f32_e32 v0, v0
	s_nop 0
	v_mul_f32_e32 v0, 0x4f7ffffe, v0
	v_cvt_u32_f32_e32 v5, v0
	v_lshl_add_u64 v[0:1], v[128:129], 0, s[4:5]
	v_mul_lo_u32 v4, v4, v5
	v_mul_hi_u32 v4, v5, v4
	v_add_u32_e32 v4, v5, v4
	s_waitcnt vmcnt(0)
	v_mul_hi_u32 v4, v3, v4
	v_mul_lo_u32 v6, v4, v2
	v_add_u32_e32 v5, 1, v3
	v_sub_u32_e32 v3, v3, v6
	v_add_u32_e32 v7, 1, v4
	v_cmp_ge_u32_e32 vcc, v3, v2
	v_sub_u32_e32 v6, v3, v2
	s_nop 0
	v_cndmask_b32_e32 v4, v4, v7, vcc
	v_cndmask_b32_e32 v3, v3, v6, vcc
	v_add_u32_e32 v6, 1, v4
	v_cmp_ge_u32_e32 vcc, v3, v2
	s_nop 1
	v_cndmask_b32_e32 v4, v4, v6, vcc
	v_mad_u64_u32 v[2:3], s[4:5], v2, v4, v[2:3]
	v_cmp_ne_u32_e32 vcc, v5, v2
	s_and_saveexec_b64 s[4:5], vcc
	s_cbranch_execz .LBB0_1250
	global_load_dword v2, v[0:1], off sc1
	s_mov_b64 s[8:9], 0
	s_waitcnt vmcnt(0)
	v_cmp_gt_u32_e32 vcc, 0x60, v2
	s_and_saveexec_b64 s[6:7], vcc
	s_cbranch_execz .LBB0_1249
	s_mov_b64 s[8:9], 0x4200
	v_lshl_add_u64 v[2:3], v[128:129], 0, s[8:9]
	s_mov_b32 s22, 1
	s_mov_b64 s[8:9], 0
	s_branch .LBB0_1242

.LBB0_1247:
	global_load_dword v5, v[0:1], off sc1
	s_add_i32 s22, s22, 1
	s_or_b64 s[14:15], s[14:15], exec
	s_waitcnt vmcnt(0)
	v_cmp_le_u32_e32 vcc, 0x60, v5
	s_orn2_b64 s[18:19], vcc, exec
	s_branch .LBB0_1241

.LBB0_1458:
	s_lshl_b32 s4, s3, 8
	s_mov_b32 s5, 0
	v_lshl_add_u64 v[4:5], v[130:131], 0, s[4:5]
	v_add_co_u32_e32 v4, vcc, 0x1000, v4
	v_mov_b32_e32 v1, 1
	s_nop 0
	v_addc_co_u32_e32 v5, vcc, 0, v5, vcc
	global_atomic_add v1, v[4:5], v1, off offset:1024 sc0
	v_cvt_f32_u32_e32 v3, v0
	v_sub_u32_e32 v4, 0, v0
	v_rcp_iflag_f32_e32 v3, v3
	s_nop 0
	v_mul_f32_e32 v3, 0x4f7ffffe, v3
	v_cvt_u32_f32_e32 v3, v3
	v_mul_lo_u32 v4, v4, v3
	v_mul_hi_u32 v4, v3, v4
	v_add_u32_e32 v3, v3, v4
	s_waitcnt vmcnt(0)
	v_mul_hi_u32 v3, v1, v3
	v_mul_lo_u32 v5, v3, v0
	v_add_u32_e32 v4, 1, v1
	v_sub_u32_e32 v1, v1, v5
	v_add_u32_e32 v6, 1, v3
	v_cmp_ge_u32_e32 vcc, v1, v0
	v_sub_u32_e32 v5, v1, v0
	s_nop 0
	v_cndmask_b32_e32 v3, v3, v6, vcc
	v_cndmask_b32_e32 v1, v1, v5, vcc
	v_add_u32_e32 v5, 1, v3
	v_cmp_ge_u32_e32 vcc, v1, v0
	s_nop 1
	v_cndmask_b32_e32 v1, v3, v5, vcc
	v_mad_u64_u32 v[0:1], s[4:5], v0, v1, v[0:1]
	v_cmp_ne_u32_e32 vcc, v4, v0
	s_and_saveexec_b64 s[4:5], vcc
	s_xor_b64 s[4:5], exec, s[4:5]
	s_cbranch_execz .LBB0_1471
	v_add_co_u32_e32 v0, vcc, 0x7000, v128
	s_nop 1
	v_addc_co_u32_e32 v1, vcc, 0, v129, vcc
	global_load_dword v0, v[0:1], off offset:1280 sc1
	s_waitcnt vmcnt(0)
	v_cmp_gt_u32_e32 vcc, 0x68, v0
	s_and_saveexec_b64 s[6:7], vcc
	s_cbranch_execz .LBB0_1470
	s_mov_b64 s[8:9], 0x7500
	s_waitcnt lgkmcnt(0)
	v_lshl_add_u64 v[2:3], v[128:129], 0, s[8:9]
	s_mov_b64 s[8:9], 0x4200
	v_lshl_add_u64 v[0:1], v[128:129], 0, s[8:9]
	s_mov_b32 s24, 1
	s_mov_b64 s[8:9], 0
	s_branch .LBB0_1462

.LBB0_1466:
	s_andn2_b64 s[14:15], s[14:15], exec
	s_and_b64 s[20:21], s[20:21], exec
	s_or_b64 s[14:15], s[14:15], s[20:21]
	s_and_saveexec_b64 s[20:21], s[18:19]
	s_cbranch_execz .LBB0_1461
	global_load_dword v4, v[2:3], off sc1
	s_add_i32 s24, s24, 1
	s_or_b64 s[14:15], s[14:15], exec
	s_waitcnt vmcnt(0)
	v_cmp_lt_u32_e32 vcc, 0x67, v4
	s_orn2_b64 s[16:17], vcc, exec
	s_branch .LBB0_1461

.LBB0_1471:
	s_andn2_saveexec_b64 s[4:5], s[4:5]
	s_cbranch_execz .LBB0_1487
	v_add_co_u32_e32 v0, vcc, 0x7000, v128
	buffer_wbl2 sc1
	s_waitcnt lgkmcnt(0)
	s_waitcnt vmcnt(0)
	v_addc_co_u32_e32 v1, vcc, 0, v129, vcc
	v_mov_b32_e32 v3, 1
	global_atomic_add v3, v[0:1], v3, off offset:1280 sc0
	v_cvt_f32_u32_e32 v0, v2
	v_sub_u32_e32 v4, 0, v2
	s_mov_b64 s[4:5], 0x7500
	s_mov_b64 s[6:7], 0
	v_rcp_iflag_f32_e32 v0, v0
	s_nop 0
	v_mul_f32_e32 v0, 0x4f7ffffe, v0
	v_cvt_u32_f32_e32 v5, v0
	v_lshl_add_u64 v[0:1], v[128:129], 0, s[4:5]
	v_mul_lo_u32 v4, v4, v5
	v_mul_hi_u32 v4, v5, v4
	v_add_u32_e32 v4, v5, v4
	s_waitcnt vmcnt(0)
	v_mul_hi_u32 v4, v3, v4
	v_mul_lo_u32 v6, v4, v2
	v_add_u32_e32 v5, 1, v3
	v_sub_u32_e32 v3, v3, v6
	v_add_u32_e32 v7, 1, v4
	v_cmp_ge_u32_e32 vcc, v3, v2
	v_sub_u32_e32 v6, v3, v2
	s_nop 0
	v_cndmask_b32_e32 v4, v4, v7, vcc
	v_cndmask_b32_e32 v3, v3, v6, vcc
	v_add_u32_e32 v6, 1, v4
	v_cmp_ge_u32_e32 vcc, v3, v2
	s_nop 1
	v_cndmask_b32_e32 v4, v4, v6, vcc
	v_mad_u64_u32 v[2:3], s[4:5], v2, v4, v[2:3]
	v_cmp_ne_u32_e32 vcc, v5, v2
	s_and_saveexec_b64 s[4:5], vcc
	s_cbranch_execz .LBB0_1484
	global_load_dword v2, v[0:1], off sc1
	s_mov_b64 s[8:9], 0
	s_waitcnt vmcnt(0)
	v_cmp_gt_u32_e32 vcc, 0x68, v2
	s_and_saveexec_b64 s[6:7], vcc
	s_cbranch_execz .LBB0_1483
	s_mov_b64 s[8:9], 0x4200
	v_lshl_add_u64 v[2:3], v[128:129], 0, s[8:9]
	s_mov_b32 s22, 1
	s_mov_b64 s[8:9], 0
	s_branch .LBB0_1476

.LBB0_1481:
	global_load_dword v5, v[0:1], off sc1
	s_add_i32 s22, s22, 1
	s_or_b64 s[14:15], s[14:15], exec
	s_waitcnt vmcnt(0)
	v_cmp_le_u32_e32 vcc, 0x68, v5
	s_orn2_b64 s[18:19], vcc, exec
	s_branch .LBB0_1475

.LBB0_1512:
	s_lshl_b32 s4, s3, 8
	s_mov_b32 s5, 0
	v_lshl_add_u64 v[4:5], v[130:131], 0, s[4:5]
	v_add_co_u32_e32 v4, vcc, 0x1000, v4
	v_mov_b32_e32 v1, 1
	s_nop 0
	v_addc_co_u32_e32 v5, vcc, 0, v5, vcc
	global_atomic_add v1, v[4:5], v1, off offset:1024 sc0
	v_cvt_f32_u32_e32 v3, v0
	v_sub_u32_e32 v4, 0, v0
	v_rcp_iflag_f32_e32 v3, v3
	s_nop 0
	v_mul_f32_e32 v3, 0x4f7ffffe, v3
	v_cvt_u32_f32_e32 v3, v3
	v_mul_lo_u32 v4, v4, v3
	v_mul_hi_u32 v4, v3, v4
	v_add_u32_e32 v3, v3, v4
	s_waitcnt vmcnt(0)
	v_mul_hi_u32 v3, v1, v3
	v_mul_lo_u32 v5, v3, v0
	v_add_u32_e32 v4, 1, v1
	v_sub_u32_e32 v1, v1, v5
	v_add_u32_e32 v6, 1, v3
	v_cmp_ge_u32_e32 vcc, v1, v0
	v_sub_u32_e32 v5, v1, v0
	s_nop 0
	v_cndmask_b32_e32 v3, v3, v6, vcc
	v_cndmask_b32_e32 v1, v1, v5, vcc
	v_add_u32_e32 v5, 1, v3
	v_cmp_ge_u32_e32 vcc, v1, v0
	s_nop 1
	v_cndmask_b32_e32 v1, v3, v5, vcc
	v_mad_u64_u32 v[0:1], s[4:5], v0, v1, v[0:1]
	v_cmp_ne_u32_e32 vcc, v4, v0
	s_and_saveexec_b64 s[4:5], vcc
	s_xor_b64 s[4:5], exec, s[4:5]
	s_cbranch_execz .LBB0_1525
	v_add_co_u32_e32 v0, vcc, 0x7000, v128
	s_nop 1
	v_addc_co_u32_e32 v1, vcc, 0, v129, vcc
	global_load_dword v0, v[0:1], off offset:1280 sc1
	s_waitcnt vmcnt(0)
	v_cmp_gt_u32_e32 vcc, 0x70, v0
	s_and_saveexec_b64 s[6:7], vcc
	s_cbranch_execz .LBB0_1524
	s_mov_b64 s[8:9], 0x7500
	s_waitcnt lgkmcnt(0)
	v_lshl_add_u64 v[2:3], v[128:129], 0, s[8:9]
	s_mov_b64 s[8:9], 0x4200
	v_lshl_add_u64 v[0:1], v[128:129], 0, s[8:9]
	s_mov_b32 s24, 1
	s_mov_b64 s[8:9], 0
	s_branch .LBB0_1516

.LBB0_1520:
	s_andn2_b64 s[14:15], s[14:15], exec
	s_and_b64 s[20:21], s[20:21], exec
	s_or_b64 s[14:15], s[14:15], s[20:21]
	s_and_saveexec_b64 s[20:21], s[18:19]
	s_cbranch_execz .LBB0_1515
	global_load_dword v4, v[2:3], off sc1
	s_add_i32 s24, s24, 1
	s_or_b64 s[14:15], s[14:15], exec
	s_waitcnt vmcnt(0)
	v_cmp_lt_u32_e32 vcc, 0x6f, v4
	s_orn2_b64 s[16:17], vcc, exec
	s_branch .LBB0_1515

.LBB0_1525:
	s_andn2_saveexec_b64 s[4:5], s[4:5]
	s_cbranch_execz .LBB0_1541
	v_add_co_u32_e32 v0, vcc, 0x7000, v128
	buffer_wbl2 sc1
	s_waitcnt lgkmcnt(0)
	s_waitcnt vmcnt(0)
	v_addc_co_u32_e32 v1, vcc, 0, v129, vcc
	v_mov_b32_e32 v3, 1
	global_atomic_add v3, v[0:1], v3, off offset:1280 sc0
	v_cvt_f32_u32_e32 v0, v2
	v_sub_u32_e32 v4, 0, v2
	s_mov_b64 s[4:5], 0x7500
	s_mov_b64 s[6:7], 0
	v_rcp_iflag_f32_e32 v0, v0
	s_nop 0
	v_mul_f32_e32 v0, 0x4f7ffffe, v0
	v_cvt_u32_f32_e32 v5, v0
	v_lshl_add_u64 v[0:1], v[128:129], 0, s[4:5]
	v_mul_lo_u32 v4, v4, v5
	v_mul_hi_u32 v4, v5, v4
	v_add_u32_e32 v4, v5, v4
	s_waitcnt vmcnt(0)
	v_mul_hi_u32 v4, v3, v4
	v_mul_lo_u32 v6, v4, v2
	v_add_u32_e32 v5, 1, v3
	v_sub_u32_e32 v3, v3, v6
	v_add_u32_e32 v7, 1, v4
	v_cmp_ge_u32_e32 vcc, v3, v2
	v_sub_u32_e32 v6, v3, v2
	s_nop 0
	v_cndmask_b32_e32 v4, v4, v7, vcc
	v_cndmask_b32_e32 v3, v3, v6, vcc
	v_add_u32_e32 v6, 1, v4
	v_cmp_ge_u32_e32 vcc, v3, v2
	s_nop 1
	v_cndmask_b32_e32 v4, v4, v6, vcc
	v_mad_u64_u32 v[2:3], s[4:5], v2, v4, v[2:3]
	v_cmp_ne_u32_e32 vcc, v5, v2
	s_and_saveexec_b64 s[4:5], vcc
	s_cbranch_execz .LBB0_1538
	global_load_dword v2, v[0:1], off sc1
	s_mov_b64 s[8:9], 0
	s_waitcnt vmcnt(0)
	v_cmp_gt_u32_e32 vcc, 0x70, v2
	s_and_saveexec_b64 s[6:7], vcc
	s_cbranch_execz .LBB0_1537
	s_mov_b64 s[8:9], 0x4200
	v_lshl_add_u64 v[2:3], v[128:129], 0, s[8:9]
	s_mov_b32 s22, 1
	s_mov_b64 s[8:9], 0
	s_branch .LBB0_1530

.LBB0_1535:
	global_load_dword v5, v[0:1], off sc1
	s_add_i32 s22, s22, 1
	s_or_b64 s[14:15], s[14:15], exec
	s_waitcnt vmcnt(0)
	v_cmp_le_u32_e32 vcc, 0x70, v5
	s_orn2_b64 s[18:19], vcc, exec
	s_branch .LBB0_1529

.LBB0_1580:
	s_lshl_b32 s4, s3, 8
	s_mov_b32 s5, 0
	v_lshl_add_u64 v[4:5], v[130:131], 0, s[4:5]
	v_add_co_u32_e32 v4, vcc, 0x1000, v4
	v_mov_b32_e32 v1, 1
	s_nop 0
	v_addc_co_u32_e32 v5, vcc, 0, v5, vcc
	global_atomic_add v1, v[4:5], v1, off offset:1024 sc0
	v_cvt_f32_u32_e32 v3, v0
	v_sub_u32_e32 v4, 0, v0
	v_rcp_iflag_f32_e32 v3, v3
	s_nop 0
	v_mul_f32_e32 v3, 0x4f7ffffe, v3
	v_cvt_u32_f32_e32 v3, v3
	v_mul_lo_u32 v4, v4, v3
	v_mul_hi_u32 v4, v3, v4
	v_add_u32_e32 v3, v3, v4
	s_waitcnt vmcnt(0)
	v_mul_hi_u32 v3, v1, v3
	v_mul_lo_u32 v5, v3, v0
	v_add_u32_e32 v4, 1, v1
	v_sub_u32_e32 v1, v1, v5
	v_add_u32_e32 v6, 1, v3
	v_cmp_ge_u32_e32 vcc, v1, v0
	v_sub_u32_e32 v5, v1, v0
	s_nop 0
	v_cndmask_b32_e32 v3, v3, v6, vcc
	v_cndmask_b32_e32 v1, v1, v5, vcc
	v_add_u32_e32 v5, 1, v3
	v_cmp_ge_u32_e32 vcc, v1, v0
	s_nop 1
	v_cndmask_b32_e32 v1, v3, v5, vcc
	v_mad_u64_u32 v[0:1], s[4:5], v0, v1, v[0:1]
	v_cmp_ne_u32_e32 vcc, v4, v0
	s_and_saveexec_b64 s[4:5], vcc
	s_xor_b64 s[4:5], exec, s[4:5]
	s_cbranch_execz .LBB0_1593
	v_add_co_u32_e32 v0, vcc, 0x7000, v128
	s_nop 1
	v_addc_co_u32_e32 v1, vcc, 0, v129, vcc
	global_load_dword v0, v[0:1], off offset:1280 sc1
	s_waitcnt vmcnt(0)
	v_cmp_gt_u32_e32 vcc, 0x78, v0
	s_and_saveexec_b64 s[6:7], vcc
	s_cbranch_execz .LBB0_1592
	s_mov_b64 s[8:9], 0x7500
	s_waitcnt lgkmcnt(0)
	v_lshl_add_u64 v[2:3], v[128:129], 0, s[8:9]
	s_mov_b64 s[8:9], 0x4200
	v_lshl_add_u64 v[0:1], v[128:129], 0, s[8:9]
	s_mov_b32 s24, 1
	s_mov_b64 s[8:9], 0
	s_branch .LBB0_1584

.LBB0_1588:
	s_andn2_b64 s[14:15], s[14:15], exec
	s_and_b64 s[20:21], s[20:21], exec
	s_or_b64 s[14:15], s[14:15], s[20:21]
	s_and_saveexec_b64 s[20:21], s[18:19]
	s_cbranch_execz .LBB0_1583
	global_load_dword v4, v[2:3], off sc1
	s_add_i32 s24, s24, 1
	s_or_b64 s[14:15], s[14:15], exec
	s_waitcnt vmcnt(0)
	v_cmp_lt_u32_e32 vcc, 0x77, v4
	s_orn2_b64 s[16:17], vcc, exec
	s_branch .LBB0_1583

.LBB0_1593:
	s_andn2_saveexec_b64 s[4:5], s[4:5]
	s_cbranch_execz .LBB0_1609
	v_add_co_u32_e32 v0, vcc, 0x7000, v128
	buffer_wbl2 sc1
	s_waitcnt lgkmcnt(0)
	s_waitcnt vmcnt(0)
	v_addc_co_u32_e32 v1, vcc, 0, v129, vcc
	v_mov_b32_e32 v3, 1
	global_atomic_add v3, v[0:1], v3, off offset:1280 sc0
	v_cvt_f32_u32_e32 v0, v2
	v_sub_u32_e32 v4, 0, v2
	s_mov_b64 s[4:5], 0x7500
	s_mov_b64 s[6:7], 0
	v_rcp_iflag_f32_e32 v0, v0
	s_nop 0
	v_mul_f32_e32 v0, 0x4f7ffffe, v0
	v_cvt_u32_f32_e32 v5, v0
	v_lshl_add_u64 v[0:1], v[128:129], 0, s[4:5]
	v_mul_lo_u32 v4, v4, v5
	v_mul_hi_u32 v4, v5, v4
	v_add_u32_e32 v4, v5, v4
	s_waitcnt vmcnt(0)
	v_mul_hi_u32 v4, v3, v4
	v_mul_lo_u32 v6, v4, v2
	v_add_u32_e32 v5, 1, v3
	v_sub_u32_e32 v3, v3, v6
	v_add_u32_e32 v7, 1, v4
	v_cmp_ge_u32_e32 vcc, v3, v2
	v_sub_u32_e32 v6, v3, v2
	s_nop 0
	v_cndmask_b32_e32 v4, v4, v7, vcc
	v_cndmask_b32_e32 v3, v3, v6, vcc
	v_add_u32_e32 v6, 1, v4
	v_cmp_ge_u32_e32 vcc, v3, v2
	s_nop 1
	v_cndmask_b32_e32 v4, v4, v6, vcc
	v_mad_u64_u32 v[2:3], s[4:5], v2, v4, v[2:3]
	v_cmp_ne_u32_e32 vcc, v5, v2
	s_and_saveexec_b64 s[4:5], vcc
	s_cbranch_execz .LBB0_1606
	global_load_dword v2, v[0:1], off sc1
	s_mov_b64 s[8:9], 0
	s_waitcnt vmcnt(0)
	v_cmp_gt_u32_e32 vcc, 0x78, v2
	s_and_saveexec_b64 s[6:7], vcc
	s_cbranch_execz .LBB0_1605
	s_mov_b64 s[8:9], 0x4200
	v_lshl_add_u64 v[2:3], v[128:129], 0, s[8:9]
	s_mov_b32 s22, 1
	s_mov_b64 s[8:9], 0
	s_branch .LBB0_1598

.LBB0_1603:
	global_load_dword v5, v[0:1], off sc1
	s_add_i32 s22, s22, 1
	s_or_b64 s[14:15], s[14:15], exec
	s_waitcnt vmcnt(0)
	v_cmp_le_u32_e32 vcc, 0x78, v5
	s_orn2_b64 s[18:19], vcc, exec
	s_branch .LBB0_1597

.LBB0_1627:
	s_lshl_b32 s4, s3, 8
	s_mov_b32 s5, 0
	v_lshl_add_u64 v[4:5], v[130:131], 0, s[4:5]
	v_add_co_u32_e32 v4, vcc, 0x1000, v4
	v_mov_b32_e32 v1, 1
	s_nop 0
	v_addc_co_u32_e32 v5, vcc, 0, v5, vcc
	global_atomic_add v1, v[4:5], v1, off offset:1024 sc0
	v_cvt_f32_u32_e32 v3, v0
	v_sub_u32_e32 v4, 0, v0
	v_rcp_iflag_f32_e32 v3, v3
	s_nop 0
	v_mul_f32_e32 v3, 0x4f7ffffe, v3
	v_cvt_u32_f32_e32 v3, v3
	v_mul_lo_u32 v4, v4, v3
	v_mul_hi_u32 v4, v3, v4
	v_add_u32_e32 v3, v3, v4
	s_waitcnt vmcnt(0)
	v_mul_hi_u32 v3, v1, v3
	v_mul_lo_u32 v5, v3, v0
	v_add_u32_e32 v4, 1, v1
	v_sub_u32_e32 v1, v1, v5
	v_add_u32_e32 v6, 1, v3
	v_cmp_ge_u32_e32 vcc, v1, v0
	v_sub_u32_e32 v5, v1, v0
	s_nop 0
	v_cndmask_b32_e32 v3, v3, v6, vcc
	v_cndmask_b32_e32 v1, v1, v5, vcc
	v_add_u32_e32 v5, 1, v3
	v_cmp_ge_u32_e32 vcc, v1, v0
	s_nop 1
	v_cndmask_b32_e32 v1, v3, v5, vcc
	v_mad_u64_u32 v[0:1], s[4:5], v0, v1, v[0:1]
	v_cmp_ne_u32_e32 vcc, v4, v0
	s_and_saveexec_b64 s[4:5], vcc
	s_xor_b64 s[4:5], exec, s[4:5]
	s_cbranch_execz .LBB0_1640
	v_add_co_u32_e32 v0, vcc, 0x7000, v128
	s_nop 1
	v_addc_co_u32_e32 v1, vcc, 0, v129, vcc
	global_load_dword v0, v[0:1], off offset:1280 sc1
	s_waitcnt vmcnt(0)
	v_cmp_gt_u32_e32 vcc, 0x80, v0
	s_and_saveexec_b64 s[6:7], vcc
	s_cbranch_execz .LBB0_1639
	s_mov_b64 s[8:9], 0x7500
	s_waitcnt lgkmcnt(0)
	v_lshl_add_u64 v[2:3], v[128:129], 0, s[8:9]
	s_mov_b64 s[8:9], 0x4200
	v_lshl_add_u64 v[0:1], v[128:129], 0, s[8:9]
	s_mov_b32 s24, 1
	s_mov_b64 s[8:9], 0
	s_branch .LBB0_1631

.LBB0_1635:
	s_andn2_b64 s[14:15], s[14:15], exec
	s_and_b64 s[20:21], s[20:21], exec
	s_or_b64 s[14:15], s[14:15], s[20:21]
	s_and_saveexec_b64 s[20:21], s[18:19]
	s_cbranch_execz .LBB0_1630
	global_load_dword v4, v[2:3], off sc1
	s_add_i32 s24, s24, 1
	s_or_b64 s[14:15], s[14:15], exec
	s_waitcnt vmcnt(0)
	v_cmp_lt_u32_e32 vcc, 0x7f, v4
	s_orn2_b64 s[16:17], vcc, exec
	s_branch .LBB0_1630

.LBB0_1640:
	s_andn2_saveexec_b64 s[4:5], s[4:5]
	s_cbranch_execz .LBB0_1656
	v_add_co_u32_e32 v0, vcc, 0x7000, v128
	buffer_wbl2 sc1
	s_waitcnt lgkmcnt(0)
	s_waitcnt vmcnt(0)
	v_addc_co_u32_e32 v1, vcc, 0, v129, vcc
	v_mov_b32_e32 v3, 1
	global_atomic_add v3, v[0:1], v3, off offset:1280 sc0
	v_cvt_f32_u32_e32 v0, v2
	v_sub_u32_e32 v4, 0, v2
	s_mov_b64 s[4:5], 0x7500
	s_mov_b64 s[6:7], 0
	v_rcp_iflag_f32_e32 v0, v0
	s_nop 0
	v_mul_f32_e32 v0, 0x4f7ffffe, v0
	v_cvt_u32_f32_e32 v5, v0
	v_lshl_add_u64 v[0:1], v[128:129], 0, s[4:5]
	v_mul_lo_u32 v4, v4, v5
	v_mul_hi_u32 v4, v5, v4
	v_add_u32_e32 v4, v5, v4
	s_waitcnt vmcnt(0)
	v_mul_hi_u32 v4, v3, v4
	v_mul_lo_u32 v6, v4, v2
	v_add_u32_e32 v5, 1, v3
	v_sub_u32_e32 v3, v3, v6
	v_add_u32_e32 v7, 1, v4
	v_cmp_ge_u32_e32 vcc, v3, v2
	v_sub_u32_e32 v6, v3, v2
	s_nop 0
	v_cndmask_b32_e32 v4, v4, v7, vcc
	v_cndmask_b32_e32 v3, v3, v6, vcc
	v_add_u32_e32 v6, 1, v4
	v_cmp_ge_u32_e32 vcc, v3, v2
	s_nop 1
	v_cndmask_b32_e32 v4, v4, v6, vcc
	v_mad_u64_u32 v[2:3], s[4:5], v2, v4, v[2:3]
	v_cmp_ne_u32_e32 vcc, v5, v2
	s_and_saveexec_b64 s[4:5], vcc
	s_cbranch_execz .LBB0_1653
	global_load_dword v2, v[0:1], off sc1
	s_mov_b64 s[8:9], 0
	s_waitcnt vmcnt(0)
	v_cmp_gt_u32_e32 vcc, 0x80, v2
	s_and_saveexec_b64 s[6:7], vcc
	s_cbranch_execz .LBB0_1652
	s_mov_b64 s[8:9], 0x4200
	v_lshl_add_u64 v[2:3], v[128:129], 0, s[8:9]
	s_mov_b32 s22, 1
	s_mov_b64 s[8:9], 0
	s_branch .LBB0_1645

.LBB0_1650:
	global_load_dword v5, v[0:1], off sc1
	s_add_i32 s22, s22, 1
	s_or_b64 s[14:15], s[14:15], exec
	s_waitcnt vmcnt(0)
	v_cmp_le_u32_e32 vcc, 0x80, v5
	s_orn2_b64 s[18:19], vcc, exec
	s_branch .LBB0_1644

.LBB0_1687:
	s_lshl_b32 s4, s3, 8
	s_mov_b32 s5, 0
	v_lshl_add_u64 v[4:5], v[130:131], 0, s[4:5]
	v_add_co_u32_e32 v4, vcc, 0x1000, v4
	v_mov_b32_e32 v1, 1
	s_nop 0
	v_addc_co_u32_e32 v5, vcc, 0, v5, vcc
	global_atomic_add v1, v[4:5], v1, off offset:1024 sc0
	v_cvt_f32_u32_e32 v3, v0
	v_sub_u32_e32 v4, 0, v0
	v_rcp_iflag_f32_e32 v3, v3
	s_nop 0
	v_mul_f32_e32 v3, 0x4f7ffffe, v3
	v_cvt_u32_f32_e32 v3, v3
	v_mul_lo_u32 v4, v4, v3
	v_mul_hi_u32 v4, v3, v4
	v_add_u32_e32 v3, v3, v4
	s_waitcnt vmcnt(0)
	v_mul_hi_u32 v3, v1, v3
	v_mul_lo_u32 v5, v3, v0
	v_add_u32_e32 v4, 1, v1
	v_sub_u32_e32 v1, v1, v5
	v_add_u32_e32 v6, 1, v3
	v_cmp_ge_u32_e32 vcc, v1, v0
	v_sub_u32_e32 v5, v1, v0
	s_nop 0
	v_cndmask_b32_e32 v3, v3, v6, vcc
	v_cndmask_b32_e32 v1, v1, v5, vcc
	v_add_u32_e32 v5, 1, v3
	v_cmp_ge_u32_e32 vcc, v1, v0
	s_nop 1
	v_cndmask_b32_e32 v1, v3, v5, vcc
	v_mad_u64_u32 v[0:1], s[4:5], v0, v1, v[0:1]
	v_cmp_ne_u32_e32 vcc, v4, v0
	s_and_saveexec_b64 s[4:5], vcc
	s_xor_b64 s[4:5], exec, s[4:5]
	s_cbranch_execz .LBB0_1700
	v_add_co_u32_e32 v0, vcc, 0x7000, v128
	s_nop 1
	v_addc_co_u32_e32 v1, vcc, 0, v129, vcc
	global_load_dword v0, v[0:1], off offset:1280 sc1
	s_waitcnt vmcnt(0)
	v_cmp_gt_u32_e32 vcc, 0x88, v0
	s_and_saveexec_b64 s[6:7], vcc
	s_cbranch_execz .LBB0_1699
	s_mov_b64 s[8:9], 0x7500
	s_waitcnt lgkmcnt(0)
	v_lshl_add_u64 v[2:3], v[128:129], 0, s[8:9]
	s_mov_b64 s[8:9], 0x4200
	v_lshl_add_u64 v[0:1], v[128:129], 0, s[8:9]
	s_mov_b32 s24, 1
	s_mov_b64 s[8:9], 0
	s_branch .LBB0_1691

.LBB0_1695:
	s_andn2_b64 s[14:15], s[14:15], exec
	s_and_b64 s[20:21], s[20:21], exec
	s_or_b64 s[14:15], s[14:15], s[20:21]
	s_and_saveexec_b64 s[20:21], s[18:19]
	s_cbranch_execz .LBB0_1690
	global_load_dword v4, v[2:3], off sc1
	s_add_i32 s24, s24, 1
	s_or_b64 s[14:15], s[14:15], exec
	s_waitcnt vmcnt(0)
	v_cmp_lt_u32_e32 vcc, 0x87, v4
	s_orn2_b64 s[16:17], vcc, exec
	s_branch .LBB0_1690

.LBB0_1700:
	s_andn2_saveexec_b64 s[4:5], s[4:5]
	s_cbranch_execz .LBB0_1716
	v_add_co_u32_e32 v0, vcc, 0x7000, v128
	buffer_wbl2 sc1
	s_waitcnt lgkmcnt(0)
	s_waitcnt vmcnt(0)
	v_addc_co_u32_e32 v1, vcc, 0, v129, vcc
	v_mov_b32_e32 v3, 1
	global_atomic_add v3, v[0:1], v3, off offset:1280 sc0
	v_cvt_f32_u32_e32 v0, v2
	v_sub_u32_e32 v4, 0, v2
	s_mov_b64 s[4:5], 0x7500
	s_mov_b64 s[6:7], 0
	v_rcp_iflag_f32_e32 v0, v0
	s_nop 0
	v_mul_f32_e32 v0, 0x4f7ffffe, v0
	v_cvt_u32_f32_e32 v5, v0
	v_lshl_add_u64 v[0:1], v[128:129], 0, s[4:5]
	v_mul_lo_u32 v4, v4, v5
	v_mul_hi_u32 v4, v5, v4
	v_add_u32_e32 v4, v5, v4
	s_waitcnt vmcnt(0)
	v_mul_hi_u32 v4, v3, v4
	v_mul_lo_u32 v6, v4, v2
	v_add_u32_e32 v5, 1, v3
	v_sub_u32_e32 v3, v3, v6
	v_add_u32_e32 v7, 1, v4
	v_cmp_ge_u32_e32 vcc, v3, v2
	v_sub_u32_e32 v6, v3, v2
	s_nop 0
	v_cndmask_b32_e32 v4, v4, v7, vcc
	v_cndmask_b32_e32 v3, v3, v6, vcc
	v_add_u32_e32 v6, 1, v4
	v_cmp_ge_u32_e32 vcc, v3, v2
	s_nop 1
	v_cndmask_b32_e32 v4, v4, v6, vcc
	v_mad_u64_u32 v[2:3], s[4:5], v2, v4, v[2:3]
	v_cmp_ne_u32_e32 vcc, v5, v2
	s_and_saveexec_b64 s[4:5], vcc
	s_cbranch_execz .LBB0_1713
	global_load_dword v2, v[0:1], off sc1
	s_mov_b64 s[8:9], 0
	s_waitcnt vmcnt(0)
	v_cmp_gt_u32_e32 vcc, 0x88, v2
	s_and_saveexec_b64 s[6:7], vcc
	s_cbranch_execz .LBB0_1712
	s_mov_b64 s[8:9], 0x4200
	v_lshl_add_u64 v[2:3], v[128:129], 0, s[8:9]
	s_mov_b32 s22, 1
	s_mov_b64 s[8:9], 0
	s_branch .LBB0_1705

.LBB0_1710:
	global_load_dword v5, v[0:1], off sc1
	s_add_i32 s22, s22, 1
	s_or_b64 s[14:15], s[14:15], exec
	s_waitcnt vmcnt(0)
	v_cmp_le_u32_e32 vcc, 0x88, v5
	s_orn2_b64 s[18:19], vcc, exec
	s_branch .LBB0_1704

.LBB0_1759:
	s_lshl_b32 s4, s3, 8
	s_mov_b32 s5, 0
	v_lshl_add_u64 v[4:5], v[130:131], 0, s[4:5]
	v_add_co_u32_e32 v4, vcc, 0x1000, v4
	v_mov_b32_e32 v1, 1
	s_nop 0
	v_addc_co_u32_e32 v5, vcc, 0, v5, vcc
	global_atomic_add v1, v[4:5], v1, off offset:1024 sc0
	v_cvt_f32_u32_e32 v3, v0
	v_sub_u32_e32 v4, 0, v0
	v_rcp_iflag_f32_e32 v3, v3
	s_nop 0
	v_mul_f32_e32 v3, 0x4f7ffffe, v3
	v_cvt_u32_f32_e32 v3, v3
	v_mul_lo_u32 v4, v4, v3
	v_mul_hi_u32 v4, v3, v4
	v_add_u32_e32 v3, v3, v4
	s_waitcnt vmcnt(0)
	v_mul_hi_u32 v3, v1, v3
	v_mul_lo_u32 v5, v3, v0
	v_add_u32_e32 v4, 1, v1
	v_sub_u32_e32 v1, v1, v5
	v_add_u32_e32 v6, 1, v3
	v_cmp_ge_u32_e32 vcc, v1, v0
	v_sub_u32_e32 v5, v1, v0
	s_nop 0
	v_cndmask_b32_e32 v3, v3, v6, vcc
	v_cndmask_b32_e32 v1, v1, v5, vcc
	v_add_u32_e32 v5, 1, v3
	v_cmp_ge_u32_e32 vcc, v1, v0
	s_nop 1
	v_cndmask_b32_e32 v1, v3, v5, vcc
	v_mad_u64_u32 v[0:1], s[4:5], v0, v1, v[0:1]
	v_cmp_ne_u32_e32 vcc, v4, v0
	s_and_saveexec_b64 s[4:5], vcc
	s_xor_b64 s[4:5], exec, s[4:5]
	s_cbranch_execz .LBB0_1772
	v_add_co_u32_e32 v0, vcc, 0x7000, v128
	s_nop 1
	v_addc_co_u32_e32 v1, vcc, 0, v129, vcc
	global_load_dword v0, v[0:1], off offset:1280 sc1
	s_waitcnt vmcnt(0)
	v_cmp_gt_u32_e32 vcc, 0x90, v0
	s_and_saveexec_b64 s[6:7], vcc
	s_cbranch_execz .LBB0_1771
	s_mov_b64 s[8:9], 0x7500
	s_waitcnt lgkmcnt(0)
	v_lshl_add_u64 v[2:3], v[128:129], 0, s[8:9]
	s_mov_b64 s[8:9], 0x4200
	v_lshl_add_u64 v[0:1], v[128:129], 0, s[8:9]
	s_mov_b32 s3, 1
	s_mov_b64 s[8:9], 0
	s_branch .LBB0_1763

.LBB0_1767:
	s_andn2_b64 s[12:13], s[12:13], exec
	s_and_b64 s[18:19], s[18:19], exec
	s_or_b64 s[12:13], s[12:13], s[18:19]
	s_and_saveexec_b64 s[18:19], s[16:17]
	s_cbranch_execz .LBB0_1762
	global_load_dword v4, v[2:3], off sc1
	s_add_i32 s3, s3, 1
	s_or_b64 s[12:13], s[12:13], exec
	s_waitcnt vmcnt(0)
	v_cmp_lt_u32_e32 vcc, 0x8f, v4
	s_orn2_b64 s[14:15], vcc, exec
	s_branch .LBB0_1762

.LBB0_1772:
	s_andn2_saveexec_b64 s[4:5], s[4:5]
	s_cbranch_execz .LBB0_1788
	v_add_co_u32_e32 v0, vcc, 0x7000, v128
	buffer_wbl2 sc1
	s_waitcnt lgkmcnt(0)
	s_waitcnt vmcnt(0)
	v_addc_co_u32_e32 v1, vcc, 0, v129, vcc
	v_mov_b32_e32 v3, 1
	global_atomic_add v3, v[0:1], v3, off offset:1280 sc0
	v_cvt_f32_u32_e32 v0, v2
	v_sub_u32_e32 v4, 0, v2
	s_mov_b64 s[4:5], 0x7500
	s_mov_b64 s[6:7], 0
	v_rcp_iflag_f32_e32 v0, v0
	s_nop 0
	v_mul_f32_e32 v0, 0x4f7ffffe, v0
	v_cvt_u32_f32_e32 v5, v0
	v_lshl_add_u64 v[0:1], v[128:129], 0, s[4:5]
	v_mul_lo_u32 v4, v4, v5
	v_mul_hi_u32 v4, v5, v4
	v_add_u32_e32 v4, v5, v4
	s_waitcnt vmcnt(0)
	v_mul_hi_u32 v4, v3, v4
	v_mul_lo_u32 v6, v4, v2
	v_add_u32_e32 v5, 1, v3
	v_sub_u32_e32 v3, v3, v6
	v_add_u32_e32 v7, 1, v4
	v_cmp_ge_u32_e32 vcc, v3, v2
	v_sub_u32_e32 v6, v3, v2
	s_nop 0
	v_cndmask_b32_e32 v4, v4, v7, vcc
	v_cndmask_b32_e32 v3, v3, v6, vcc
	v_add_u32_e32 v6, 1, v4
	v_cmp_ge_u32_e32 vcc, v3, v2
	s_nop 1
	v_cndmask_b32_e32 v4, v4, v6, vcc
	v_mad_u64_u32 v[2:3], s[4:5], v2, v4, v[2:3]
	v_cmp_ne_u32_e32 vcc, v5, v2
	s_and_saveexec_b64 s[4:5], vcc
	s_cbranch_execz .LBB0_1785
	global_load_dword v2, v[0:1], off sc1
	s_mov_b64 s[8:9], 0
	s_waitcnt vmcnt(0)
	v_cmp_gt_u32_e32 vcc, 0x90, v2
	s_and_saveexec_b64 s[6:7], vcc
	s_cbranch_execz .LBB0_1784
	s_mov_b64 s[8:9], 0x4200
	v_lshl_add_u64 v[2:3], v[128:129], 0, s[8:9]
	s_mov_b32 s3, 1
	s_mov_b64 s[8:9], 0
	s_branch .LBB0_1777

.LBB0_1782:
	global_load_dword v5, v[0:1], off sc1
	s_add_i32 s3, s3, 1
	s_or_b64 s[12:13], s[12:13], exec
	s_waitcnt vmcnt(0)
	v_cmp_le_u32_e32 vcc, 0x90, v5
	s_orn2_b64 s[16:17], vcc, exec
	s_branch .LBB0_1776
